# all seams after S1 XCD-local: converted-weight readiness via converter-done counters (S2/S7/S10), cross-XCD write-after-read hazards via deferred arrival checks before each tile's first stores (S3/S6/
# speedup vs baseline: 1.0088x; 1.0088x over previous
; __device__ __forceinline__ int lane_id_() { int l; asm volatile("v_mbcnt_lo_u32_b32 %0, -1, 0\n\tv_mbcnt_hi_u32_b32 %0, -1, %0" : "=v"(l)); return l; }
; __device__ __forceinline__ unsigned xb_ld(unsigned* p)              { return __hip_atomic_load(p, __ATOMIC_RELAXED, __HIP_MEMORY_SCOPE_AGENT); }
; __device__ __forceinline__ unsigned xb_add(unsigned* p, unsigned v) { return __hip_atomic_fetch_add(p, v, __ATOMIC_RELAXED, __HIP_MEMORY_SCOPE_AGENT); }
; #define XB_SPIN(cond, bar) do { unsigned _sp = 0; while (cond) { __builtin_amdgcn_s_sleep(1); \
;     if ((++_sp & 255u) == 0u) { if (xb_ld(&(bar)[XB_TMO])) break; if (_sp > XB_SPIN_CAP) { atomicAdd(&(bar)[XB_TMO], 1u); break; } } } } while (0)
; __device__ __forceinline__ void xcd_barrier(const XcdBarrier& b, int wave_s) {
;     asm volatile("s_waitcnt vmcnt(0)" ::: "memory");
;     __syncthreads();
;     if (wave_s == 0 && lane_id_() == 0) {
;         unsigned* bar = b.bar;
;         __builtin_amdgcn_s_waitcnt(0);
;         unsigned nloc = b.st[0], nx = b.st[1];
;         if (nloc == 0u) { xcd_barrier_complete(bar, b.x, nloc, nx); b.st[0] = nloc; b.st[1] = nx; }
;         const unsigned old = xb_add(&bar[XB_XSUB(b.x)], 1u);
;         const unsigned gen = old / nloc;
;         if (old + 1u == (gen + 1u) * nloc) {
;             __builtin_amdgcn_fence(__ATOMIC_RELEASE, "agent");
;             asm volatile("s_waitcnt vmcnt(0)" ::: "memory");
;             const unsigned og = xb_add(&bar[XB_TOP], 1u);
;             const unsigned tg = og / nx;
;             if (og + 1u == (tg + 1u) * nx) xb_add(&bar[XB_TOPGEN], 1u);
;             else XB_SPIN(xb_ld(&bar[XB_TOPGEN]) == tg, bar);
;             __builtin_amdgcn_fence(__ATOMIC_ACQUIRE, "agent");
;             xb_add(&bar[XB_XGEN(b.x)], 1u);
;             asm volatile("s_waitcnt vmcnt(0)" ::: "memory");
;         } else {
;             XB_SPIN(xb_ld(&bar[XB_XGEN(b.x)]) == gen, bar);
;             __builtin_amdgcn_fence(__ATOMIC_ACQUIRE, "agent");
;             asm volatile("s_waitcnt vmcnt(0)" ::: "memory");
;         }
.LBB0_252:
	s_waitcnt vmcnt(0)
	v_cndmask_b32_e64 v0, 0, 1, s[4:5]
	v_cmp_ne_u32_e64 s[2:3], 1, v0
	s_andn2_b64 vcc, exec, s[4:5]
	s_waitcnt vmcnt(0)
	s_barrier
	s_cbranch_vccnz .LBB0_306
	v_mbcnt_lo_u32_b32 v0, -1, 0
	v_mbcnt_hi_u32_b32 v0, -1, v0
	s_nop 0
	v_cmp_eq_u32_e32 vcc, 0, v0
	s_and_saveexec_b64 s[4:5], vcc
	s_cbranch_execz .LBB0_305
	s_cmp_eq_u32 s101, 1
	s_cbranch_scc0 .Lglob_S2
	s_cmpk_lt_u32 s33, 0x80
	s_cbranch_scc1 .Lnc_S2
	v_mov_b32_e32 v0, 0x5100
	v_mov_b32_e32 v1, 1
	global_atomic_add v0, v1, s[44:45]
.Lnc_S2:
	s_and_b32 s98, s33, 7
	s_lshl_b32 s99, s98, 2
	s_addk_i32 s99, 0x4800
	v_mov_b32_e32 v3, s99
	s_lshl_b32 s98, s98, 8
	s_addk_i32 s98, 0x4000
	v_mov_b32_e32 v0, s98
	v_mov_b32_e32 v1, 1
	global_atomic_add v2, v0, v1, s[44:45] sc0
	v_mov_b32_e32 v5, 0x5100
	global_load_dword v5, v5, s[44:45] sc1
	buffer_inv sc1
	s_waitcnt vmcnt(2)
	v_readfirstlane_b32 s98, v2
	s_nop 3
	s_add_u32 s99, s98, 1
	s_and_b32 s99, s99, 31
	s_lshr_b32 s98, s98, 5
	s_cmp_eq_u32 s99, 0
	s_cbranch_scc0 .Llw_S2
	global_atomic_add v3, v1, s[44:45]
	s_branch .Lla_S2

; __device__ __forceinline__ int lane_id_() { int l; asm volatile("v_mbcnt_lo_u32_b32 %0, -1, 0\n\tv_mbcnt_hi_u32_b32 %0, -1, %0" : "=v"(l)); return l; }
; __device__ __forceinline__ unsigned xb_ld(unsigned* p)              { return __hip_atomic_load(p, __ATOMIC_RELAXED, __HIP_MEMORY_SCOPE_AGENT); }
; __device__ __forceinline__ unsigned xb_add(unsigned* p, unsigned v) { return __hip_atomic_fetch_add(p, v, __ATOMIC_RELAXED, __HIP_MEMORY_SCOPE_AGENT); }
; #define XB_SPIN(cond, bar) do { unsigned _sp = 0; while (cond) { __builtin_amdgcn_s_sleep(1); \
;     if ((++_sp & 255u) == 0u) { if (xb_ld(&(bar)[XB_TMO])) break; if (_sp > XB_SPIN_CAP) { atomicAdd(&(bar)[XB_TMO], 1u); break; } } } } while (0)
; __device__ __forceinline__ void xcd_barrier(const XcdBarrier& b, int wave_s) {
;     asm volatile("s_waitcnt vmcnt(0)" ::: "memory");
;     __syncthreads();
;     if (wave_s == 0 && lane_id_() == 0) {
;         unsigned* bar = b.bar;
;         __builtin_amdgcn_s_waitcnt(0);
;         unsigned nloc = b.st[0], nx = b.st[1];
;         if (nloc == 0u) { xcd_barrier_complete(bar, b.x, nloc, nx); b.st[0] = nloc; b.st[1] = nx; }
;         const unsigned old = xb_add(&bar[XB_XSUB(b.x)], 1u);
;         const unsigned gen = old / nloc;
;         if (old + 1u == (gen + 1u) * nloc) {
;             __builtin_amdgcn_fence(__ATOMIC_RELEASE, "agent");
;             asm volatile("s_waitcnt vmcnt(0)" ::: "memory");
;             const unsigned og = xb_add(&bar[XB_TOP], 1u);
;             const unsigned tg = og / nx;
;             if (og + 1u == (tg + 1u) * nx) xb_add(&bar[XB_TOPGEN], 1u);
;             else XB_SPIN(xb_ld(&bar[XB_TOPGEN]) == tg, bar);
;             __builtin_amdgcn_fence(__ATOMIC_ACQUIRE, "agent");
;             xb_add(&bar[XB_XGEN(b.x)], 1u);
;             asm volatile("s_waitcnt vmcnt(0)" ::: "memory");
;         } else {
;             XB_SPIN(xb_ld(&bar[XB_XGEN(b.x)]) == gen, bar);
;             __builtin_amdgcn_fence(__ATOMIC_ACQUIRE, "agent");
;             asm volatile("s_waitcnt vmcnt(0)" ::: "memory");
;         }
.Lla_S2:
	s_waitcnt vmcnt(0)
	v_readfirstlane_b32 s100, v5
	s_nop 3
	s_cmp_ge_u32 s100, 0x80
	s_cbranch_scc1 .Lcd_S2
	v_mov_b32_e32 v0, 0x5100
	s_mov_b32 s99, 0
.Lcw_S2:
	global_load_dword v2, v0, s[44:45] sc1
	s_waitcnt vmcnt(0)
	v_readfirstlane_b32 s100, v2
	s_nop 3
	s_cmp_ge_u32 s100, 0x80
	s_cbranch_scc1 .Lcd_S2
	s_add_u32 s99, s99, 1
	s_cmp_lt_u32 s99, 0x4000
	s_cbranch_scc1 .Lcw_S2
.Lcd_S2:
	s_branch .LBB0_305

; #define PG8_WAIT_V8_STRICT() asm volatile("s_waitcnt vmcnt(8)" ::: "memory")
; template <class Epi, class Sched, bool ALIGN_EPI = false, bool SP2 = false>
; __device__ __forceinline__ void gemm_phase(PG8_LAS unsigned char* lds, const Gemm g, const Sched& S, const Epi& E, int wave_s) {
;     ...
;         for (int t = peeled ? 2 : 0; t < nt; t += 2) {
;             const bool last = (t == nt - 2);
;             const char* a1 = cA + (size_t)(t + 1) * kstep;
;             const char* a2 = last ? nA : cA + (size_t)(t + 2) * kstep; const char* b2 = last ? nB : cB + (size_t)(t + 2) * kstep;
;             const char* a3 = a2 + kstep; const char* b3 = b2 + kstep;
;             if (last && has_next) S.a_ready(nxt);
;             if constexpr (SP2) {
;             PG8_SP2_PAIR(PG8_WAIT_V8_STRICT);
.Lwsb_0:
	v_add_u32_e32 v151, s78, v146
	v_add_u32_e32 v150, s79, v146
	ds_read_b128 v[152:155], v151
	ds_read_b128 v[156:159], v151 offset:1024
	ds_read_b128 v[160:163], v151 offset:2048
	ds_read_b128 v[164:167], v151 offset:3072
	ds_read_b128 v[168:171], v150
	ds_read_b128 v[176:179], v150 offset:1024
	ds_read_b128 v[180:183], v150 offset:2048
	ds_read_b128 v[184:187], v150 offset:3072
	s_add_u32 s8, s52, 0x100
	s_addc_u32 s9, s53, 0
	s_cmp_eq_u32 s96, 12
	s_cselect_b32 s42, s93, s8
	s_cselect_b32 s43, s82, s9
	s_cselect_b32 s40, s95, s97
	s_cselect_b32 s41, s94, vcc_lo
	s_add_u32 s38, s42, 0x80
	s_addc_u32 s39, s43, 0
	s_add_u32 s52, s52, 0x40080
	s_addc_u32 s53, s53, 0
	s_add_i32 s91, s35, 0xc000
	ds_read_b128 v[188:191], v149
	ds_read_b128 v[192:195], v149 offset:1024
	ds_read_b128 v[196:199], v149 offset:2048
	ds_read_b128 v[200:203], v149 offset:3072
	ds_read_b128 v[204:207], v149 offset:4096
	ds_read_b128 v[208:211], v149 offset:5120
	ds_read_b128 v[212:215], v149 offset:6144
	ds_read_b128 v[216:219], v149 offset:7168
	s_mov_b32 m0, s91
	s_add_i32 s10, s35, 0xe000
	global_load_lds_dwordx4 v132, s[52:53]
	s_mov_b32 m0, s10
	s_nop 0
	global_load_lds_dwordx4 v136, s[52:53]
	s_waitcnt vmcnt(8)
	s_waitcnt lgkmcnt(0)
	s_barrier
	s_waitcnt lgkmcnt(0)
	v_mfma_f32_16x16x32_bf16 v[128:131], v[152:155], v[188:191], v[128:131]
	v_mfma_f32_16x16x32_bf16 v[124:127], v[160:163], v[188:191], v[124:127]
	v_mfma_f32_16x16x32_bf16 v[112:115], v[152:155], v[196:199], v[112:115]
	v_mfma_f32_16x16x32_bf16 v[108:111], v[160:163], v[196:199], v[108:111]
	v_mfma_f32_16x16x32_bf16 v[96:99], v[152:155], v[204:207], v[96:99]
	v_mfma_f32_16x16x32_bf16 v[92:95], v[160:163], v[204:207], v[92:95]
	v_mfma_f32_16x16x32_bf16 v[80:83], v[152:155], v[212:215], v[80:83]
	v_mfma_f32_16x16x32_bf16 v[76:79], v[160:163], v[212:215], v[76:79]
	v_mfma_f32_16x16x32_bf16 v[128:131], v[156:159], v[192:195], v[128:131]
	v_mfma_f32_16x16x32_bf16 v[124:127], v[164:167], v[192:195], v[124:127]
	v_mfma_f32_16x16x32_bf16 v[112:115], v[156:159], v[200:203], v[112:115]
	v_mfma_f32_16x16x32_bf16 v[108:111], v[164:167], v[200:203], v[108:111]
	v_mfma_f32_16x16x32_bf16 v[96:99], v[156:159], v[208:211], v[96:99]
	v_mfma_f32_16x16x32_bf16 v[92:95], v[164:167], v[208:211], v[92:95]
	v_mfma_f32_16x16x32_bf16 v[80:83], v[156:159], v[216:219], v[80:83]
	v_mfma_f32_16x16x32_bf16 v[76:79], v[164:167], v[216:219], v[76:79]
	v_mfma_f32_16x16x32_bf16 v[120:123], v[168:171], v[188:191], v[120:123]
	v_mfma_f32_16x16x32_bf16 v[116:119], v[180:183], v[188:191], v[116:119]
	v_mfma_f32_16x16x32_bf16 v[104:107], v[168:171], v[196:199], v[104:107]
	v_mfma_f32_16x16x32_bf16 v[100:103], v[180:183], v[196:199], v[100:103]
	v_mfma_f32_16x16x32_bf16 v[88:91], v[168:171], v[204:207], v[88:91]
	v_mfma_f32_16x16x32_bf16 v[84:87], v[180:183], v[204:207], v[84:87]
	v_mfma_f32_16x16x32_bf16 v[72:75], v[168:171], v[212:215], v[72:75]
	v_mfma_f32_16x16x32_bf16 v[68:71], v[180:183], v[212:215], v[68:71]
	v_mfma_f32_16x16x32_bf16 v[120:123], v[176:179], v[192:195], v[120:123]
	v_mfma_f32_16x16x32_bf16 v[116:119], v[184:187], v[192:195], v[116:119]
	v_mfma_f32_16x16x32_bf16 v[104:107], v[176:179], v[200:203], v[104:107]
	v_mfma_f32_16x16x32_bf16 v[100:103], v[184:187], v[200:203], v[100:103]
	v_mfma_f32_16x16x32_bf16 v[88:91], v[176:179], v[208:211], v[88:91]
	v_mfma_f32_16x16x32_bf16 v[84:87], v[184:187], v[208:211], v[84:87]
	v_mfma_f32_16x16x32_bf16 v[72:75], v[176:179], v[216:219], v[72:75]
	v_mfma_f32_16x16x32_bf16 v[68:71], v[184:187], v[216:219], v[68:71]
	s_barrier
	s_setprio 1
	s_mov_b64 s[52:53], s[40:41]
	s_add_i32 s90, s78, s58
	ds_read_b128 v[188:191], v149 offset:16384
	ds_read_b128 v[192:195], v149 offset:17408
	ds_read_b128 v[196:199], v149 offset:18432
	ds_read_b128 v[200:203], v149 offset:19456
	ds_read_b128 v[204:207], v149 offset:20480
	ds_read_b128 v[208:211], v149 offset:21504
	ds_read_b128 v[212:215], v149 offset:22528
	ds_read_b128 v[216:219], v149 offset:23552
	s_mov_b32 m0, s90
	s_add_i32 s25, s90, 0x2000
	global_load_lds_dwordx4 v134, s[52:53]
	s_mov_b64 s[98:99], s[52:53]
	s_add_u32 s52, s40, 0x40000
	s_mov_b32 m0, s25
	s_addc_u32 s53, s41, 0
	s_add_i32 s27, s79, s58
	global_load_lds_dwordx4 v138, s[98:99]
	s_mov_b32 m0, s27
	s_add_i32 s88, s27, 0x2000
	global_load_lds_dwordx4 v134, s[52:53]
	s_mov_b64 s[98:99], s[52:53]
	s_mov_b32 m0, s88
	s_mov_b64 s[52:53], s[42:43]
	global_load_lds_dwordx4 v138, s[98:99]
	s_mov_b32 m0, s35
	s_nop 0
	global_load_lds_dwordx4 v132, s[52:53]
	s_mov_b32 m0, s37
	s_nop 0
	global_load_lds_dwordx4 v136, s[52:53]
	s_setprio 0
	s_waitcnt vmcnt(8)
	s_waitcnt lgkmcnt(0)
	s_barrier
	s_waitcnt lgkmcnt(0)
	v_mfma_f32_16x16x32_bf16 v[64:67], v[152:155], v[188:191], v[64:67]
	v_mfma_f32_16x16x32_bf16 v[60:63], v[160:163], v[188:191], v[60:63]
	v_mfma_f32_16x16x32_bf16 v[48:51], v[152:155], v[196:199], v[48:51]
	v_mfma_f32_16x16x32_bf16 v[44:47], v[160:163], v[196:199], v[44:47]
	v_mfma_f32_16x16x32_bf16 v[32:35], v[152:155], v[204:207], v[32:35]
	v_mfma_f32_16x16x32_bf16 v[28:31], v[160:163], v[204:207], v[28:31]
	v_mfma_f32_16x16x32_bf16 v[16:19], v[152:155], v[212:215], v[16:19]
	v_mfma_f32_16x16x32_bf16 v[12:15], v[160:163], v[212:215], v[12:15]
	v_mfma_f32_16x16x32_bf16 v[64:67], v[156:159], v[192:195], v[64:67]
	v_mfma_f32_16x16x32_bf16 v[60:63], v[164:167], v[192:195], v[60:63]
	v_mfma_f32_16x16x32_bf16 v[48:51], v[156:159], v[200:203], v[48:51]
	v_mfma_f32_16x16x32_bf16 v[44:47], v[164:167], v[200:203], v[44:47]
	v_mfma_f32_16x16x32_bf16 v[32:35], v[156:159], v[208:211], v[32:35]
	v_mfma_f32_16x16x32_bf16 v[28:31], v[164:167], v[208:211], v[28:31]
	v_mfma_f32_16x16x32_bf16 v[16:19], v[156:159], v[216:219], v[16:19]
	v_mfma_f32_16x16x32_bf16 v[12:15], v[164:167], v[216:219], v[12:15]
	v_mfma_f32_16x16x32_bf16 v[56:59], v[168:171], v[188:191], v[56:59]
	v_mfma_f32_16x16x32_bf16 v[52:55], v[180:183], v[188:191], v[52:55]
	v_mfma_f32_16x16x32_bf16 v[40:43], v[168:171], v[196:199], v[40:43]
	v_mfma_f32_16x16x32_bf16 v[36:39], v[180:183], v[196:199], v[36:39]
	v_mfma_f32_16x16x32_bf16 v[24:27], v[168:171], v[204:207], v[24:27]
	v_mfma_f32_16x16x32_bf16 v[20:23], v[180:183], v[204:207], v[20:23]
	v_mfma_f32_16x16x32_bf16 v[8:11], v[168:171], v[212:215], v[8:11]
	v_mfma_f32_16x16x32_bf16 v[2:5], v[180:183], v[212:215], v[4:7]
	v_mfma_f32_16x16x32_bf16 v[56:59], v[176:179], v[192:195], v[56:59]
	v_mfma_f32_16x16x32_bf16 v[52:55], v[184:187], v[192:195], v[52:55]
	v_mfma_f32_16x16x32_bf16 v[40:43], v[176:179], v[200:203], v[40:43]
	v_mfma_f32_16x16x32_bf16 v[36:39], v[184:187], v[200:203], v[36:39]
	v_mfma_f32_16x16x32_bf16 v[24:27], v[176:179], v[208:211], v[24:27]
	v_mfma_f32_16x16x32_bf16 v[20:23], v[184:187], v[208:211], v[20:23]
	v_mfma_f32_16x16x32_bf16 v[8:11], v[176:179], v[216:219], v[8:11]
	v_mfma_f32_16x16x32_bf16 v[2:5], v[184:187], v[216:219], v[2:5]
	s_barrier
	s_add_i32 s92, 0, 0x18000
	s_add_i32 s52, 0, 0x1c000
	v_add_u32_e32 v152, s92, v146
	v_add_u32_e32 v153, s52, v146
	ds_read_b128 v[154:157], v152
	ds_read_b128 v[158:161], v152 offset:1024
	ds_read_b128 v[162:165], v152 offset:2048
	ds_read_b128 v[166:169], v152 offset:3072
	ds_read_b128 v[170:173], v153
	ds_read_b128 v[176:179], v153 offset:1024
	ds_read_b128 v[180:183], v153 offset:2048
	ds_read_b128 v[184:187], v153 offset:3072
	s_add_u32 s42, s42, 0x40000
	s_addc_u32 s43, s43, 0
	s_mov_b32 m0, s60
	ds_read_b128 v[188:191], v149 offset:32768
	ds_read_b128 v[192:195], v149 offset:33792
	ds_read_b128 v[196:199], v149 offset:34816
	ds_read_b128 v[200:203], v149 offset:35840
	ds_read_b128 v[204:207], v149 offset:36864
	ds_read_b128 v[208:211], v149 offset:37888
	ds_read_b128 v[212:215], v149 offset:38912
	ds_read_b128 v[216:219], v149 offset:39936
	s_nop 0
	global_load_lds_dwordx4 v132, s[42:43]
	s_mov_b32 m0, s61
	s_nop 0
	global_load_lds_dwordx4 v136, s[42:43]
	s_waitcnt vmcnt(8)
	s_waitcnt lgkmcnt(0)
	s_barrier
	s_waitcnt lgkmcnt(0)
	v_mfma_f32_16x16x32_bf16 v[128:131], v[154:157], v[188:191], v[128:131]
	v_mfma_f32_16x16x32_bf16 v[124:127], v[162:165], v[188:191], v[124:127]
	v_mfma_f32_16x16x32_bf16 v[112:115], v[154:157], v[196:199], v[112:115]
	v_mfma_f32_16x16x32_bf16 v[108:111], v[162:165], v[196:199], v[108:111]
	v_mfma_f32_16x16x32_bf16 v[96:99], v[154:157], v[204:207], v[96:99]
	v_mfma_f32_16x16x32_bf16 v[92:95], v[162:165], v[204:207], v[92:95]
	v_mfma_f32_16x16x32_bf16 v[80:83], v[154:157], v[212:215], v[80:83]
	v_mfma_f32_16x16x32_bf16 v[76:79], v[162:165], v[212:215], v[76:79]
	v_mfma_f32_16x16x32_bf16 v[128:131], v[158:161], v[192:195], v[128:131]
	v_mfma_f32_16x16x32_bf16 v[124:127], v[166:169], v[192:195], v[124:127]
	v_mfma_f32_16x16x32_bf16 v[112:115], v[158:161], v[200:203], v[112:115]
	v_mfma_f32_16x16x32_bf16 v[108:111], v[166:169], v[200:203], v[108:111]
	v_mfma_f32_16x16x32_bf16 v[96:99], v[158:161], v[208:211], v[96:99]
	v_mfma_f32_16x16x32_bf16 v[92:95], v[166:169], v[208:211], v[92:95]
	v_mfma_f32_16x16x32_bf16 v[80:83], v[158:161], v[216:219], v[80:83]
	v_mfma_f32_16x16x32_bf16 v[76:79], v[166:169], v[216:219], v[76:79]
	v_mfma_f32_16x16x32_bf16 v[120:123], v[170:173], v[188:191], v[120:123]
	v_mfma_f32_16x16x32_bf16 v[116:119], v[180:183], v[188:191], v[116:119]
	v_mfma_f32_16x16x32_bf16 v[104:107], v[170:173], v[196:199], v[104:107]
	v_mfma_f32_16x16x32_bf16 v[100:103], v[180:183], v[196:199], v[100:103]
	v_mfma_f32_16x16x32_bf16 v[88:91], v[170:173], v[204:207], v[88:91]
	v_mfma_f32_16x16x32_bf16 v[84:87], v[180:183], v[204:207], v[84:87]
	v_mfma_f32_16x16x32_bf16 v[72:75], v[170:173], v[212:215], v[72:75]
	v_mfma_f32_16x16x32_bf16 v[68:71], v[180:183], v[212:215], v[68:71]
	v_mfma_f32_16x16x32_bf16 v[120:123], v[176:179], v[192:195], v[120:123]
	v_mfma_f32_16x16x32_bf16 v[116:119], v[184:187], v[192:195], v[116:119]
	v_mfma_f32_16x16x32_bf16 v[104:107], v[176:179], v[200:203], v[104:107]
	v_mfma_f32_16x16x32_bf16 v[100:103], v[184:187], v[200:203], v[100:103]
	v_mfma_f32_16x16x32_bf16 v[88:91], v[176:179], v[208:211], v[88:91]
	v_mfma_f32_16x16x32_bf16 v[84:87], v[184:187], v[208:211], v[84:87]
	v_mfma_f32_16x16x32_bf16 v[72:75], v[176:179], v[216:219], v[72:75]
	v_mfma_f32_16x16x32_bf16 v[68:71], v[184:187], v[216:219], v[68:71]
	s_barrier
; #define PG8_LDA(dst, b, h) do { _Pragma("unroll") for (int m = 0; m < 4; ++m) _Pragma("unroll") for (int k = 0; k < 2; ++k) dst[m][k] = *(const PG8_LAS bf16x8*)(lds + PG8_SA(b, h) + aoff + m * 2048 + k * 1024); } while (0)
; template <class Epi, class Sched, bool ALIGN_EPI = false, bool SP2 = false>
; __device__ __forceinline__ void gemm_phase(PG8_LAS unsigned char* lds, const Gemm g, const Sched& S, const Epi& E, int wave_s) {
;     ...
;         for (int t = peeled ? 2 : 0; t < nt; t += 2) {
;             const bool last = (t == nt - 2);
;             const char* a1 = cA + (size_t)(t + 1) * kstep;
;             const char* a2 = last ? nA : cA + (size_t)(t + 2) * kstep; const char* b2 = last ? nB : cB + (size_t)(t + 2) * kstep;
;             const char* a3 = a2 + kstep; const char* b3 = b2 + kstep;
;             if (last && has_next) S.a_ready(nxt);
;             if constexpr (SP2) {
;             PG8_SP2_PAIR(PG8_WAIT_V8_STRICT);
;             } else {
;             PG8_LDB(B0, 0, 0); PG8_SCHED; PG8_LDA(At, 0, 0); PG8_STAGE(PG8_SA(1, 1), a1 + hstep, voffA);
;             PG8_WAIT_L(8); PG8_BAR; PG8_WAIT_L(0); PG8_MMA(0, 0, At, B0); PG8_BAR; PG8_SCHED;
;             PG8_LDB(B1, 0, 1); PG8_STAGE(PG8_SB(0, 0), b2, voffB);
;             PG8_BAR; PG8_WAIT_L(0); PG8_MMA(0, 1, At, B1); PG8_BAR;
;             PG8_LDA(At, 0, 1); PG8_STAGE(PG8_SA(0, 0), a2, voffA);
;             PG8_BAR; PG8_WAIT_L(0); PG8_MMA(1, 0, At, B0); PG8_BAR; PG8_SCHED;
;             PG8_STAGE(PG8_SB(0, 1), b2 + hstep, voffB);
;             PG8_WAIT_V(6); PG8_BAR; PG8_MMA(1, 1, At, B1); PG8_BAR;
;             PG8_LDB(B0, 1, 0); PG8_SCHED; PG8_LDA(At, 1, 0); PG8_STAGE(PG8_SA(0, 1), a2 + hstep, voffA);
;             PG8_WAIT_L(8); PG8_BAR; PG8_WAIT_L(0); PG8_MMA(0, 0, At, B0); PG8_BAR; PG8_SCHED;
;             PG8_LDB(B1, 1, 1); PG8_STAGE(PG8_SB(1, 0), b3, voffB);
;             PG8_BAR; PG8_WAIT_L(0); PG8_MMA(0, 1, At, B1); PG8_BAR;
;             PG8_LDA(At, 1, 1); PG8_STAGE(PG8_SA(1, 0), a3, voffA);
;             PG8_BAR; PG8_WAIT_L(0); PG8_MMA(1, 0, At, B0); PG8_BAR; PG8_SCHED;
;             PG8_STAGE(PG8_SB(1, 1), b3 + hstep, voffB);
;             PG8_WAIT_V(6); PG8_BAR; PG8_MMA(1, 1, At, B1); PG8_BAR;
;             }
;         }
;         if constexpr (ALIGN_EPI) { if (wr == 0) PG8_BAR; }
;         if constexpr (!Epi::AFTER_DRAIN) { E(acc, cur, wr, wc, fr, fq, lds, wid); S.done(cur); }
	s_setprio 1
	s_add_u32 s42, s40, 0x80
	s_addc_u32 s43, s41, 0
	s_add_i32 s92, s92, s58
	ds_read_b128 v[188:191], v149 offset:49152
	ds_read_b128 v[192:195], v149 offset:50176
	ds_read_b128 v[196:199], v149 offset:51200
	ds_read_b128 v[200:203], v149 offset:52224
	ds_read_b128 v[204:207], v149 offset:53248
	ds_read_b128 v[208:211], v149 offset:54272
	ds_read_b128 v[212:215], v149 offset:55296
	ds_read_b128 v[216:219], v149 offset:56320
	s_mov_b32 m0, s92
	s_nop 0
	global_load_lds_dwordx4 v134, s[42:43]
	s_mov_b64 s[98:99], s[42:43]
	s_add_i32 s42, s92, 0x2000
	s_add_u32 s40, s40, 0x40080
	s_mov_b32 m0, s42
	s_addc_u32 s41, s41, 0
	s_add_i32 s43, s52, s58
	global_load_lds_dwordx4 v138, s[98:99]
	s_mov_b32 m0, s43
	s_add_i32 s89, s43, 0x2000
	global_load_lds_dwordx4 v134, s[40:41]
	s_mov_b32 m0, s89
	s_nop 0
	global_load_lds_dwordx4 v138, s[40:41]
	s_mov_b32 m0, s63
	s_nop 0
	global_load_lds_dwordx4 v132, s[38:39]
	s_mov_b32 m0, s72
	s_nop 0
	global_load_lds_dwordx4 v136, s[38:39]
	s_setprio 0
	s_waitcnt vmcnt(8)
	s_waitcnt lgkmcnt(0)
	s_barrier
	s_waitcnt lgkmcnt(0)
	v_mfma_f32_16x16x32_bf16 v[64:67], v[154:157], v[188:191], v[64:67]
	v_mfma_f32_16x16x32_bf16 v[60:63], v[162:165], v[188:191], v[60:63]
	v_mfma_f32_16x16x32_bf16 v[48:51], v[154:157], v[196:199], v[48:51]
	v_mfma_f32_16x16x32_bf16 v[44:47], v[162:165], v[196:199], v[44:47]
	v_mfma_f32_16x16x32_bf16 v[32:35], v[154:157], v[204:207], v[32:35]
	v_mfma_f32_16x16x32_bf16 v[28:31], v[162:165], v[204:207], v[28:31]
	v_mfma_f32_16x16x32_bf16 v[16:19], v[154:157], v[212:215], v[16:19]
	v_mfma_f32_16x16x32_bf16 v[12:15], v[162:165], v[212:215], v[12:15]
	v_mfma_f32_16x16x32_bf16 v[64:67], v[158:161], v[192:195], v[64:67]
	v_mfma_f32_16x16x32_bf16 v[60:63], v[166:169], v[192:195], v[60:63]
	v_mfma_f32_16x16x32_bf16 v[48:51], v[158:161], v[200:203], v[48:51]
	v_mfma_f32_16x16x32_bf16 v[44:47], v[166:169], v[200:203], v[44:47]
	v_mfma_f32_16x16x32_bf16 v[32:35], v[158:161], v[208:211], v[32:35]
	v_mfma_f32_16x16x32_bf16 v[28:31], v[166:169], v[208:211], v[28:31]
	v_mfma_f32_16x16x32_bf16 v[16:19], v[158:161], v[216:219], v[16:19]
	v_mfma_f32_16x16x32_bf16 v[12:15], v[166:169], v[216:219], v[12:15]
	v_mfma_f32_16x16x32_bf16 v[56:59], v[170:173], v[188:191], v[56:59]
	v_mfma_f32_16x16x32_bf16 v[52:55], v[180:183], v[188:191], v[52:55]
	v_mfma_f32_16x16x32_bf16 v[40:43], v[170:173], v[196:199], v[40:43]
	v_mfma_f32_16x16x32_bf16 v[36:39], v[180:183], v[196:199], v[36:39]
	v_mfma_f32_16x16x32_bf16 v[24:27], v[170:173], v[204:207], v[24:27]
	v_mfma_f32_16x16x32_bf16 v[20:23], v[180:183], v[204:207], v[20:23]
	v_mfma_f32_16x16x32_bf16 v[6:9], v[170:173], v[212:215], v[8:11]
	v_mfma_f32_16x16x32_bf16 v[2:5], v[180:183], v[212:215], v[2:5]
	v_mfma_f32_16x16x32_bf16 v[56:59], v[176:179], v[192:195], v[56:59]
	v_mfma_f32_16x16x32_bf16 v[52:55], v[184:187], v[192:195], v[52:55]
	v_mfma_f32_16x16x32_bf16 v[40:43], v[176:179], v[200:203], v[40:43]
	v_mfma_f32_16x16x32_bf16 v[36:39], v[184:187], v[200:203], v[36:39]
	v_mfma_f32_16x16x32_bf16 v[24:27], v[176:179], v[208:211], v[24:27]
	v_mfma_f32_16x16x32_bf16 v[20:23], v[184:187], v[208:211], v[20:23]
	v_mfma_f32_16x16x32_bf16 v[8:11], v[176:179], v[216:219], v[6:9]
	v_mfma_f32_16x16x32_bf16 v[4:7], v[184:187], v[216:219], v[2:5]
	s_barrier
	s_add_i32 s96, s96, 2
	s_add_u32 s97, s97, 0x100
	s_addc_u32 vcc_lo, vcc_lo, 0
	s_cmp_gt_u32 s96, 13
	s_mov_b64 s[52:53], s[8:9]
	s_cbranch_scc0 .LBB0_419
	s_and_b64 vcc, exec, s[16:17]
	s_cbranch_vccz .LBB0_422
	s_cmp_eq_u32 s101, 1
	s_cbranch_scc0 .Lwok_0
	v_mbcnt_lo_u32_b32 v188, -1, 0
	v_mbcnt_hi_u32_b32 v188, -1, v188
	v_lshlrev_b32_e32 v188, 2, v188
	v_add_u32_e32 v189, 0x23400, v188
	ds_read_b32 v189, v189
	s_waitcnt lgkmcnt(0)
	v_cmp_gt_u32_e32 vcc, 3, v189
	s_nop 3
	s_and_b32 vcc_lo, vcc_lo, 0xff
	s_cmp_eq_u32 vcc_lo, 0
	s_cbranch_scc1 .Lwok_0
	s_mov_b32 s100, 0

; #define PG8_WAIT_V8_STRICT() asm volatile("s_waitcnt vmcnt(8)" ::: "memory")
; template <class Epi, class Sched, bool ALIGN_EPI = false, bool SP2 = false>
; __device__ __forceinline__ void gemm_phase(PG8_LAS unsigned char* lds, const Gemm g, const Sched& S, const Epi& E, int wave_s) {
;     ...
;         for (int t = peeled ? 2 : 0; t < nt; t += 2) {
;             const bool last = (t == nt - 2);
;             const char* a1 = cA + (size_t)(t + 1) * kstep;
;             const char* a2 = last ? nA : cA + (size_t)(t + 2) * kstep; const char* b2 = last ? nB : cB + (size_t)(t + 2) * kstep;
;             const char* a3 = a2 + kstep; const char* b3 = b2 + kstep;
;             if (last && has_next) S.a_ready(nxt);
;             if constexpr (SP2) {
;             PG8_SP2_PAIR(PG8_WAIT_V8_STRICT);
.Lwsb_1:
	v_add_u32_e32 v151, s82, v146
	v_add_u32_e32 v150, s87, v146
	ds_read_b128 v[152:155], v151
	ds_read_b128 v[156:159], v151 offset:1024
	ds_read_b128 v[160:163], v151 offset:2048
	ds_read_b128 v[164:167], v151 offset:3072
	ds_read_b128 v[168:171], v150
	ds_read_b128 v[176:179], v150 offset:1024
	ds_read_b128 v[180:183], v150 offset:2048
	ds_read_b128 v[184:187], v150 offset:3072
	s_add_u32 s30, s40, 0x100
	s_addc_u32 s31, s41, 0
	s_cmp_eq_u32 s95, 12
	s_cselect_b32 s38, s92, s30
	s_cselect_b32 s39, s91, s31
	s_cselect_b32 s36, s94, s96
	s_cselect_b32 s37, s93, s6
	s_add_u32 s34, s38, 0x80
	s_addc_u32 s35, s39, 0
	s_add_u32 s40, s40, 0x40080
	s_addc_u32 s41, s41, 0
	s_add_i32 s90, s72, 0xc000
	ds_read_b128 v[188:191], v149
	ds_read_b128 v[192:195], v149 offset:1024
	ds_read_b128 v[196:199], v149 offset:2048
	ds_read_b128 v[200:203], v149 offset:3072
	ds_read_b128 v[204:207], v149 offset:4096
	ds_read_b128 v[208:211], v149 offset:5120
	ds_read_b128 v[212:215], v149 offset:6144
	ds_read_b128 v[216:219], v149 offset:7168
	s_mov_b32 m0, s90
	s_add_i32 s10, s72, 0xe000
	global_load_lds_dwordx4 v138, s[40:41]
	s_mov_b32 m0, s10
	s_nop 0
	global_load_lds_dwordx4 v134, s[40:41]
	s_waitcnt vmcnt(8)
	s_waitcnt lgkmcnt(0)
	s_barrier
	s_waitcnt lgkmcnt(0)
	v_mfma_f32_16x16x32_bf16 v[124:127], v[152:155], v[188:191], v[124:127]
	v_mfma_f32_16x16x32_bf16 v[116:119], v[160:163], v[188:191], v[116:119]
	v_mfma_f32_16x16x32_bf16 v[108:111], v[152:155], v[196:199], v[108:111]
	v_mfma_f32_16x16x32_bf16 v[100:103], v[160:163], v[196:199], v[100:103]
	v_mfma_f32_16x16x32_bf16 v[92:95], v[152:155], v[204:207], v[92:95]
	v_mfma_f32_16x16x32_bf16 v[84:87], v[160:163], v[204:207], v[84:87]
	v_mfma_f32_16x16x32_bf16 v[76:79], v[152:155], v[212:215], v[76:79]
	v_mfma_f32_16x16x32_bf16 v[60:63], v[160:163], v[212:215], v[60:63]
	v_mfma_f32_16x16x32_bf16 v[124:127], v[156:159], v[192:195], v[124:127]
	v_mfma_f32_16x16x32_bf16 v[116:119], v[164:167], v[192:195], v[116:119]
	v_mfma_f32_16x16x32_bf16 v[108:111], v[156:159], v[200:203], v[108:111]
	v_mfma_f32_16x16x32_bf16 v[100:103], v[164:167], v[200:203], v[100:103]
	v_mfma_f32_16x16x32_bf16 v[92:95], v[156:159], v[208:211], v[92:95]
	v_mfma_f32_16x16x32_bf16 v[84:87], v[164:167], v[208:211], v[84:87]
	v_mfma_f32_16x16x32_bf16 v[76:79], v[156:159], v[216:219], v[76:79]
	v_mfma_f32_16x16x32_bf16 v[60:63], v[164:167], v[216:219], v[60:63]
	v_mfma_f32_16x16x32_bf16 v[128:131], v[168:171], v[188:191], v[128:131]
	v_mfma_f32_16x16x32_bf16 v[120:123], v[180:183], v[188:191], v[120:123]
	v_mfma_f32_16x16x32_bf16 v[112:115], v[168:171], v[196:199], v[112:115]
	v_mfma_f32_16x16x32_bf16 v[104:107], v[180:183], v[196:199], v[104:107]
	v_mfma_f32_16x16x32_bf16 v[96:99], v[168:171], v[204:207], v[96:99]
	v_mfma_f32_16x16x32_bf16 v[88:91], v[180:183], v[204:207], v[88:91]
	v_mfma_f32_16x16x32_bf16 v[80:83], v[168:171], v[212:215], v[80:83]
	v_mfma_f32_16x16x32_bf16 v[68:71], v[180:183], v[212:215], v[68:71]
	v_mfma_f32_16x16x32_bf16 v[128:131], v[176:179], v[192:195], v[128:131]
	v_mfma_f32_16x16x32_bf16 v[120:123], v[184:187], v[192:195], v[120:123]
	v_mfma_f32_16x16x32_bf16 v[112:115], v[176:179], v[200:203], v[112:115]
	v_mfma_f32_16x16x32_bf16 v[104:107], v[184:187], v[200:203], v[104:107]
	v_mfma_f32_16x16x32_bf16 v[96:99], v[176:179], v[208:211], v[96:99]
	v_mfma_f32_16x16x32_bf16 v[88:91], v[184:187], v[208:211], v[88:91]
	v_mfma_f32_16x16x32_bf16 v[80:83], v[176:179], v[216:219], v[80:83]
	v_mfma_f32_16x16x32_bf16 v[68:71], v[184:187], v[216:219], v[68:71]
	s_barrier
	s_setprio 1
	s_mov_b64 s[40:41], s[36:37]
	s_add_i32 s61, s82, s42
	ds_read_b128 v[188:191], v149 offset:16384
	ds_read_b128 v[192:195], v149 offset:17408
	ds_read_b128 v[196:199], v149 offset:18432
	ds_read_b128 v[200:203], v149 offset:19456
	ds_read_b128 v[204:207], v149 offset:20480
	ds_read_b128 v[208:211], v149 offset:21504
	ds_read_b128 v[212:215], v149 offset:22528
	ds_read_b128 v[216:219], v149 offset:23552
	s_mov_b32 m0, s61
	s_add_i32 s21, s61, 0x2000
	global_load_lds_dwordx4 v136, s[40:41]
	s_mov_b64 s[98:99], s[40:41]
	s_add_u32 s40, s36, 0x40000
	s_mov_b32 m0, s21
	s_addc_u32 s41, s37, 0
	s_add_i32 s23, s87, s42
	global_load_lds_dwordx4 v132, s[98:99]
	s_mov_b32 m0, s23
	s_add_i32 s60, s23, 0x2000
	global_load_lds_dwordx4 v136, s[40:41]
	s_mov_b64 s[98:99], s[40:41]
	s_mov_b32 m0, s60
	s_mov_b64 s[40:41], s[38:39]
	global_load_lds_dwordx4 v132, s[98:99]
	s_mov_b32 m0, s72
	s_nop 0
	global_load_lds_dwordx4 v138, s[40:41]
	s_mov_b32 m0, s73
	s_nop 0
	global_load_lds_dwordx4 v134, s[40:41]
	s_setprio 0
	s_waitcnt vmcnt(8)
	s_waitcnt lgkmcnt(0)
	s_barrier
	s_waitcnt lgkmcnt(0)
	v_mfma_f32_16x16x32_bf16 v[64:67], v[152:155], v[188:191], v[64:67]
	v_mfma_f32_16x16x32_bf16 v[52:55], v[160:163], v[188:191], v[52:55]
	v_mfma_f32_16x16x32_bf16 v[44:47], v[152:155], v[196:199], v[44:47]
	v_mfma_f32_16x16x32_bf16 v[36:39], v[160:163], v[196:199], v[36:39]
	v_mfma_f32_16x16x32_bf16 v[28:31], v[152:155], v[204:207], v[28:31]
	v_mfma_f32_16x16x32_bf16 v[20:23], v[160:163], v[204:207], v[20:23]
	v_mfma_f32_16x16x32_bf16 v[12:15], v[152:155], v[212:215], v[12:15]
	v_mfma_f32_16x16x32_bf16 v[2:5], v[160:163], v[212:215], v[4:7]
	v_mfma_f32_16x16x32_bf16 v[64:67], v[156:159], v[192:195], v[64:67]
	v_mfma_f32_16x16x32_bf16 v[52:55], v[164:167], v[192:195], v[52:55]
	v_mfma_f32_16x16x32_bf16 v[44:47], v[156:159], v[200:203], v[44:47]
	v_mfma_f32_16x16x32_bf16 v[36:39], v[164:167], v[200:203], v[36:39]
	v_mfma_f32_16x16x32_bf16 v[28:31], v[156:159], v[208:211], v[28:31]
	v_mfma_f32_16x16x32_bf16 v[20:23], v[164:167], v[208:211], v[20:23]
	v_mfma_f32_16x16x32_bf16 v[12:15], v[156:159], v[216:219], v[12:15]
	v_mfma_f32_16x16x32_bf16 v[2:5], v[164:167], v[216:219], v[2:5]
	v_mfma_f32_16x16x32_bf16 v[72:75], v[168:171], v[188:191], v[72:75]
	v_mfma_f32_16x16x32_bf16 v[56:59], v[180:183], v[188:191], v[56:59]
	v_mfma_f32_16x16x32_bf16 v[48:51], v[168:171], v[196:199], v[48:51]
	v_mfma_f32_16x16x32_bf16 v[40:43], v[180:183], v[196:199], v[40:43]
	v_mfma_f32_16x16x32_bf16 v[32:35], v[168:171], v[204:207], v[32:35]
	v_mfma_f32_16x16x32_bf16 v[24:27], v[180:183], v[204:207], v[24:27]
	v_mfma_f32_16x16x32_bf16 v[16:19], v[168:171], v[212:215], v[16:19]
	v_mfma_f32_16x16x32_bf16 v[6:9], v[180:183], v[212:215], v[8:11]
	v_mfma_f32_16x16x32_bf16 v[72:75], v[176:179], v[192:195], v[72:75]
	v_mfma_f32_16x16x32_bf16 v[56:59], v[184:187], v[192:195], v[56:59]
	v_mfma_f32_16x16x32_bf16 v[48:51], v[176:179], v[200:203], v[48:51]
	v_mfma_f32_16x16x32_bf16 v[40:43], v[184:187], v[200:203], v[40:43]
	v_mfma_f32_16x16x32_bf16 v[32:35], v[176:179], v[208:211], v[32:35]
	v_mfma_f32_16x16x32_bf16 v[24:27], v[184:187], v[208:211], v[24:27]
	v_mfma_f32_16x16x32_bf16 v[16:19], v[176:179], v[216:219], v[16:19]
	v_mfma_f32_16x16x32_bf16 v[8:11], v[184:187], v[216:219], v[6:9]
	s_barrier
	s_add_i32 s7, 0, 0x18000
	s_add_i32 s86, 0, 0x1c000
	v_add_u32_e32 v152, s7, v146
	v_add_u32_e32 v153, s86, v146
	ds_read_b128 v[154:157], v152
	ds_read_b128 v[158:161], v152 offset:1024
	ds_read_b128 v[162:165], v152 offset:2048
	ds_read_b128 v[166:169], v152 offset:3072
	ds_read_b128 v[170:173], v153
	ds_read_b128 v[176:179], v153 offset:1024
	ds_read_b128 v[180:183], v153 offset:2048
	ds_read_b128 v[184:187], v153 offset:3072
	s_add_u32 s38, s38, 0x40000
	s_addc_u32 s39, s39, 0
	s_mov_b32 m0, s74
	ds_read_b128 v[188:191], v149 offset:32768
	ds_read_b128 v[192:195], v149 offset:33792
	ds_read_b128 v[196:199], v149 offset:34816
	ds_read_b128 v[200:203], v149 offset:35840
	ds_read_b128 v[204:207], v149 offset:36864
	ds_read_b128 v[208:211], v149 offset:37888
	ds_read_b128 v[212:215], v149 offset:38912
	ds_read_b128 v[216:219], v149 offset:39936
	s_nop 0
	global_load_lds_dwordx4 v138, s[38:39]
	s_mov_b32 m0, s75
	s_nop 0
	global_load_lds_dwordx4 v134, s[38:39]
	s_waitcnt vmcnt(8)
	s_waitcnt lgkmcnt(0)
	s_barrier
	s_waitcnt lgkmcnt(0)
	v_mfma_f32_16x16x32_bf16 v[124:127], v[154:157], v[188:191], v[124:127]
	v_mfma_f32_16x16x32_bf16 v[116:119], v[162:165], v[188:191], v[116:119]
	v_mfma_f32_16x16x32_bf16 v[108:111], v[154:157], v[196:199], v[108:111]
	v_mfma_f32_16x16x32_bf16 v[100:103], v[162:165], v[196:199], v[100:103]
	v_mfma_f32_16x16x32_bf16 v[92:95], v[154:157], v[204:207], v[92:95]
	v_mfma_f32_16x16x32_bf16 v[84:87], v[162:165], v[204:207], v[84:87]
	v_mfma_f32_16x16x32_bf16 v[76:79], v[154:157], v[212:215], v[76:79]
	v_mfma_f32_16x16x32_bf16 v[60:63], v[162:165], v[212:215], v[60:63]
	v_mfma_f32_16x16x32_bf16 v[124:127], v[158:161], v[192:195], v[124:127]
	v_mfma_f32_16x16x32_bf16 v[116:119], v[166:169], v[192:195], v[116:119]
	v_mfma_f32_16x16x32_bf16 v[108:111], v[158:161], v[200:203], v[108:111]
	v_mfma_f32_16x16x32_bf16 v[100:103], v[166:169], v[200:203], v[100:103]
	v_mfma_f32_16x16x32_bf16 v[92:95], v[158:161], v[208:211], v[92:95]
	v_mfma_f32_16x16x32_bf16 v[84:87], v[166:169], v[208:211], v[84:87]
	v_mfma_f32_16x16x32_bf16 v[76:79], v[158:161], v[216:219], v[76:79]
	v_mfma_f32_16x16x32_bf16 v[60:63], v[166:169], v[216:219], v[60:63]
	v_mfma_f32_16x16x32_bf16 v[128:131], v[170:173], v[188:191], v[128:131]
	v_mfma_f32_16x16x32_bf16 v[120:123], v[180:183], v[188:191], v[120:123]
	v_mfma_f32_16x16x32_bf16 v[112:115], v[170:173], v[196:199], v[112:115]
	v_mfma_f32_16x16x32_bf16 v[104:107], v[180:183], v[196:199], v[104:107]
	v_mfma_f32_16x16x32_bf16 v[96:99], v[170:173], v[204:207], v[96:99]
	v_mfma_f32_16x16x32_bf16 v[88:91], v[180:183], v[204:207], v[88:91]
	v_mfma_f32_16x16x32_bf16 v[80:83], v[170:173], v[212:215], v[80:83]
	v_mfma_f32_16x16x32_bf16 v[68:71], v[180:183], v[212:215], v[68:71]
	v_mfma_f32_16x16x32_bf16 v[128:131], v[176:179], v[192:195], v[128:131]
	v_mfma_f32_16x16x32_bf16 v[120:123], v[184:187], v[192:195], v[120:123]
	v_mfma_f32_16x16x32_bf16 v[112:115], v[176:179], v[200:203], v[112:115]
	v_mfma_f32_16x16x32_bf16 v[104:107], v[184:187], v[200:203], v[104:107]
	v_mfma_f32_16x16x32_bf16 v[96:99], v[176:179], v[208:211], v[96:99]
	v_mfma_f32_16x16x32_bf16 v[88:91], v[184:187], v[208:211], v[88:91]
	v_mfma_f32_16x16x32_bf16 v[80:83], v[176:179], v[216:219], v[80:83]
	v_mfma_f32_16x16x32_bf16 v[68:71], v[184:187], v[216:219], v[68:71]
	s_barrier
; #define PG8_LDA(dst, b, h) do { _Pragma("unroll") for (int m = 0; m < 4; ++m) _Pragma("unroll") for (int k = 0; k < 2; ++k) dst[m][k] = *(const PG8_LAS bf16x8*)(lds + PG8_SA(b, h) + aoff + m * 2048 + k * 1024); } while (0)
; template <class Epi, class Sched, bool ALIGN_EPI = false, bool SP2 = false>
; __device__ __forceinline__ void gemm_phase(PG8_LAS unsigned char* lds, const Gemm g, const Sched& S, const Epi& E, int wave_s) {
;     ...
;         for (int t = peeled ? 2 : 0; t < nt; t += 2) {
;             const bool last = (t == nt - 2);
;             const char* a1 = cA + (size_t)(t + 1) * kstep;
;             const char* a2 = last ? nA : cA + (size_t)(t + 2) * kstep; const char* b2 = last ? nB : cB + (size_t)(t + 2) * kstep;
;             const char* a3 = a2 + kstep; const char* b3 = b2 + kstep;
;             if (last && has_next) S.a_ready(nxt);
;             if constexpr (SP2) {
;             PG8_SP2_PAIR(PG8_WAIT_V8_STRICT);
;             } else {
;             PG8_LDB(B0, 0, 0); PG8_SCHED; PG8_LDA(At, 0, 0); PG8_STAGE(PG8_SA(1, 1), a1 + hstep, voffA);
;             PG8_WAIT_L(8); PG8_BAR; PG8_WAIT_L(0); PG8_MMA(0, 0, At, B0); PG8_BAR; PG8_SCHED;
;             PG8_LDB(B1, 0, 1); PG8_STAGE(PG8_SB(0, 0), b2, voffB);
;             PG8_BAR; PG8_WAIT_L(0); PG8_MMA(0, 1, At, B1); PG8_BAR;
;             PG8_LDA(At, 0, 1); PG8_STAGE(PG8_SA(0, 0), a2, voffA);
;             PG8_BAR; PG8_WAIT_L(0); PG8_MMA(1, 0, At, B0); PG8_BAR; PG8_SCHED;
;             PG8_STAGE(PG8_SB(0, 1), b2 + hstep, voffB);
;             PG8_WAIT_V(6); PG8_BAR; PG8_MMA(1, 1, At, B1); PG8_BAR;
;             PG8_LDB(B0, 1, 0); PG8_SCHED; PG8_LDA(At, 1, 0); PG8_STAGE(PG8_SA(0, 1), a2 + hstep, voffA);
;             PG8_WAIT_L(8); PG8_BAR; PG8_WAIT_L(0); PG8_MMA(0, 0, At, B0); PG8_BAR; PG8_SCHED;
;             PG8_LDB(B1, 1, 1); PG8_STAGE(PG8_SB(1, 0), b3, voffB);
;             PG8_BAR; PG8_WAIT_L(0); PG8_MMA(0, 1, At, B1); PG8_BAR;
;             PG8_LDA(At, 1, 1); PG8_STAGE(PG8_SA(1, 0), a3, voffA);
;             PG8_BAR; PG8_WAIT_L(0); PG8_MMA(1, 0, At, B0); PG8_BAR; PG8_SCHED;
;             PG8_STAGE(PG8_SB(1, 1), b3 + hstep, voffB);
;             PG8_WAIT_V(6); PG8_BAR; PG8_MMA(1, 1, At, B1); PG8_BAR;
;             }
;         }
;         if constexpr (ALIGN_EPI) { if (wr == 0) PG8_BAR; }
;         if constexpr (!Epi::AFTER_DRAIN) { E(acc, cur, wr, wc, fr, fq, lds, wid); S.done(cur); }
	s_setprio 1
	s_add_u32 s40, s36, 0x80
	s_addc_u32 s41, s37, 0
	s_add_i32 s39, s7, s42
	ds_read_b128 v[188:191], v149 offset:49152
	ds_read_b128 v[192:195], v149 offset:50176
	ds_read_b128 v[196:199], v149 offset:51200
	ds_read_b128 v[200:203], v149 offset:52224
	ds_read_b128 v[204:207], v149 offset:53248
	ds_read_b128 v[208:211], v149 offset:54272
	ds_read_b128 v[212:215], v149 offset:55296
	ds_read_b128 v[216:219], v149 offset:56320
	s_mov_b32 m0, s39
	s_add_i32 s38, s39, 0x2000
	global_load_lds_dwordx4 v136, s[40:41]
	s_mov_b64 s[98:99], s[40:41]
	s_add_u32 s40, s36, 0x40080
	s_mov_b32 m0, s38
	s_addc_u32 s41, s37, 0
	s_add_i32 s36, s86, s42
	global_load_lds_dwordx4 v132, s[98:99]
	s_mov_b32 m0, s36
	s_add_i32 s37, s36, 0x2000
	global_load_lds_dwordx4 v136, s[40:41]
	s_mov_b32 m0, s37
	s_nop 0
	global_load_lds_dwordx4 v132, s[40:41]
	s_mov_b32 m0, s76
	s_nop 0
	global_load_lds_dwordx4 v138, s[34:35]
	s_mov_b32 m0, s77
	s_nop 0
	global_load_lds_dwordx4 v134, s[34:35]
	s_setprio 0
	s_waitcnt vmcnt(8)
	s_waitcnt lgkmcnt(0)
	s_barrier
	s_waitcnt lgkmcnt(0)
	v_mfma_f32_16x16x32_bf16 v[64:67], v[154:157], v[188:191], v[64:67]
	v_mfma_f32_16x16x32_bf16 v[52:55], v[162:165], v[188:191], v[52:55]
	v_mfma_f32_16x16x32_bf16 v[44:47], v[154:157], v[196:199], v[44:47]
	v_mfma_f32_16x16x32_bf16 v[36:39], v[162:165], v[196:199], v[36:39]
	v_mfma_f32_16x16x32_bf16 v[28:31], v[154:157], v[204:207], v[28:31]
	v_mfma_f32_16x16x32_bf16 v[20:23], v[162:165], v[204:207], v[20:23]
	v_mfma_f32_16x16x32_bf16 v[12:15], v[154:157], v[212:215], v[12:15]
	v_mfma_f32_16x16x32_bf16 v[2:5], v[162:165], v[212:215], v[2:5]
	v_mfma_f32_16x16x32_bf16 v[64:67], v[158:161], v[192:195], v[64:67]
	v_mfma_f32_16x16x32_bf16 v[52:55], v[166:169], v[192:195], v[52:55]
	v_mfma_f32_16x16x32_bf16 v[44:47], v[158:161], v[200:203], v[44:47]
	v_mfma_f32_16x16x32_bf16 v[36:39], v[166:169], v[200:203], v[36:39]
	v_mfma_f32_16x16x32_bf16 v[28:31], v[158:161], v[208:211], v[28:31]
	v_mfma_f32_16x16x32_bf16 v[20:23], v[166:169], v[208:211], v[20:23]
	v_mfma_f32_16x16x32_bf16 v[12:15], v[158:161], v[216:219], v[12:15]
	v_mfma_f32_16x16x32_bf16 v[4:7], v[166:169], v[216:219], v[2:5]
	v_mfma_f32_16x16x32_bf16 v[72:75], v[170:173], v[188:191], v[72:75]
	v_mfma_f32_16x16x32_bf16 v[56:59], v[180:183], v[188:191], v[56:59]
	v_mfma_f32_16x16x32_bf16 v[48:51], v[170:173], v[196:199], v[48:51]
	v_mfma_f32_16x16x32_bf16 v[40:43], v[180:183], v[196:199], v[40:43]
	v_mfma_f32_16x16x32_bf16 v[32:35], v[170:173], v[204:207], v[32:35]
	v_mfma_f32_16x16x32_bf16 v[24:27], v[180:183], v[204:207], v[24:27]
	v_mfma_f32_16x16x32_bf16 v[16:19], v[170:173], v[212:215], v[16:19]
	v_mfma_f32_16x16x32_bf16 v[8:11], v[180:183], v[212:215], v[8:11]
	v_mfma_f32_16x16x32_bf16 v[72:75], v[176:179], v[192:195], v[72:75]
	v_mfma_f32_16x16x32_bf16 v[56:59], v[184:187], v[192:195], v[56:59]
	v_mfma_f32_16x16x32_bf16 v[48:51], v[176:179], v[200:203], v[48:51]
	v_mfma_f32_16x16x32_bf16 v[40:43], v[184:187], v[200:203], v[40:43]
	v_mfma_f32_16x16x32_bf16 v[32:35], v[176:179], v[208:211], v[32:35]
	v_mfma_f32_16x16x32_bf16 v[24:27], v[184:187], v[208:211], v[24:27]
	v_mfma_f32_16x16x32_bf16 v[16:19], v[176:179], v[216:219], v[16:19]
	v_mfma_f32_16x16x32_bf16 v[8:11], v[184:187], v[216:219], v[8:11]
	s_barrier
	s_add_i32 s95, s95, 2
	s_add_u32 s96, s96, 0x100
	s_addc_u32 s6, s6, 0
	s_cmp_gt_u32 s95, 13
	s_mov_b64 s[40:41], s[30:31]
	s_cbranch_scc0 .LBB0_912
	s_and_b64 vcc, exec, s[18:19]
	s_cbranch_vccz .LBB0_915
	s_cmp_eq_u32 s101, 1
	s_cbranch_scc0 .Lwok_1
	v_mbcnt_lo_u32_b32 v188, -1, 0
	v_mbcnt_hi_u32_b32 v188, -1, v188
	v_lshlrev_b32_e32 v188, 2, v188
	v_add_u32_e32 v189, 0x23400, v188
	ds_read_b32 v189, v189
	s_waitcnt lgkmcnt(0)
	v_cmp_gt_u32_e32 vcc, 6, v189
	s_nop 3
	s_and_b32 vcc_lo, vcc_lo, 0xff
	s_cmp_eq_u32 vcc_lo, 0
	s_cbranch_scc1 .Lwok_1
	s_mov_b32 s100, 0

; __device__ __forceinline__ int lane_id_() { int l; asm volatile("v_mbcnt_lo_u32_b32 %0, -1, 0\n\tv_mbcnt_hi_u32_b32 %0, -1, %0" : "=v"(l)); return l; }
; __device__ __forceinline__ unsigned xb_ld(unsigned* p)              { return __hip_atomic_load(p, __ATOMIC_RELAXED, __HIP_MEMORY_SCOPE_AGENT); }
; __device__ __forceinline__ unsigned xb_add(unsigned* p, unsigned v) { return __hip_atomic_fetch_add(p, v, __ATOMIC_RELAXED, __HIP_MEMORY_SCOPE_AGENT); }
; #define XB_SPIN(cond, bar) do { unsigned _sp = 0; while (cond) { __builtin_amdgcn_s_sleep(1); \
;     if ((++_sp & 255u) == 0u) { if (xb_ld(&(bar)[XB_TMO])) break; if (_sp > XB_SPIN_CAP) { atomicAdd(&(bar)[XB_TMO], 1u); break; } } } } while (0)
; __device__ __forceinline__ void xcd_barrier(const XcdBarrier& b, int wave_s) {
;     asm volatile("s_waitcnt vmcnt(0)" ::: "memory");
;     __syncthreads();
;     if (wave_s == 0 && lane_id_() == 0) {
;         unsigned* bar = b.bar;
;         __builtin_amdgcn_s_waitcnt(0);
;         unsigned nloc = b.st[0], nx = b.st[1];
;         if (nloc == 0u) { xcd_barrier_complete(bar, b.x, nloc, nx); b.st[0] = nloc; b.st[1] = nx; }
;         const unsigned old = xb_add(&bar[XB_XSUB(b.x)], 1u);
;         const unsigned gen = old / nloc;
;         if (old + 1u == (gen + 1u) * nloc) {
;             __builtin_amdgcn_fence(__ATOMIC_RELEASE, "agent");
;             asm volatile("s_waitcnt vmcnt(0)" ::: "memory");
;             const unsigned og = xb_add(&bar[XB_TOP], 1u);
;             const unsigned tg = og / nx;
;             if (og + 1u == (tg + 1u) * nx) xb_add(&bar[XB_TOPGEN], 1u);
;             else XB_SPIN(xb_ld(&bar[XB_TOPGEN]) == tg, bar);
;             __builtin_amdgcn_fence(__ATOMIC_ACQUIRE, "agent");
;             xb_add(&bar[XB_XGEN(b.x)], 1u);
;             asm volatile("s_waitcnt vmcnt(0)" ::: "memory");
;         } else {
;             XB_SPIN(xb_ld(&bar[XB_XGEN(b.x)]) == gen, bar);
;             __builtin_amdgcn_fence(__ATOMIC_ACQUIRE, "agent");
;             asm volatile("s_waitcnt vmcnt(0)" ::: "memory");
;         }
.LBB0_1111:
	s_waitcnt vmcnt(0)
	s_and_b64 vcc, exec, s[2:3]
	s_waitcnt vmcnt(0)
	s_barrier
	s_cbranch_vccnz .LBB0_1165
	v_mbcnt_lo_u32_b32 v0, -1, 0
	v_mbcnt_hi_u32_b32 v0, -1, v0
	s_nop 0
	v_cmp_eq_u32_e32 vcc, 0, v0
	s_and_saveexec_b64 s[8:9], vcc
	s_cbranch_execz .LBB0_1164
	s_cmp_eq_u32 s101, 1
	s_cbranch_scc0 .Lglob_S7
	s_cmpk_lt_u32 s33, 0x80
	s_cbranch_scc1 .Lnc_S7
	v_mov_b32_e32 v0, 0x5104
	v_mov_b32_e32 v1, 1
	global_atomic_add v0, v1, s[44:45]
.Lnc_S7:
	s_and_b32 s98, s33, 7
	s_lshl_b32 s99, s98, 2
	s_addk_i32 s99, 0x4800
	v_mov_b32_e32 v3, s99
	s_lshl_b32 s98, s98, 8
	s_addk_i32 s98, 0x4000
	v_mov_b32_e32 v0, s98
	v_mov_b32_e32 v1, 1
	global_atomic_add v2, v0, v1, s[44:45] sc0
	v_mov_b32_e32 v5, 0x5104
	global_load_dword v5, v5, s[44:45] sc1
	buffer_inv sc1
	s_waitcnt vmcnt(2)
	v_readfirstlane_b32 s98, v2
	s_nop 3
	s_add_u32 s99, s98, 1
	s_and_b32 s99, s99, 31
	s_lshr_b32 s98, s98, 5
	s_cmp_eq_u32 s99, 0
	s_cbranch_scc0 .Llw_S7
	global_atomic_add v3, v1, s[44:45]
	s_branch .Lla_S7

; __device__ __forceinline__ int lane_id_() { int l; asm volatile("v_mbcnt_lo_u32_b32 %0, -1, 0\n\tv_mbcnt_hi_u32_b32 %0, -1, %0" : "=v"(l)); return l; }
; __device__ __forceinline__ unsigned xb_ld(unsigned* p)              { return __hip_atomic_load(p, __ATOMIC_RELAXED, __HIP_MEMORY_SCOPE_AGENT); }
; __device__ __forceinline__ unsigned xb_add(unsigned* p, unsigned v) { return __hip_atomic_fetch_add(p, v, __ATOMIC_RELAXED, __HIP_MEMORY_SCOPE_AGENT); }
; #define XB_SPIN(cond, bar) do { unsigned _sp = 0; while (cond) { __builtin_amdgcn_s_sleep(1); \
;     if ((++_sp & 255u) == 0u) { if (xb_ld(&(bar)[XB_TMO])) break; if (_sp > XB_SPIN_CAP) { atomicAdd(&(bar)[XB_TMO], 1u); break; } } } } while (0)
; __device__ __forceinline__ void xcd_barrier(const XcdBarrier& b, int wave_s) {
;     asm volatile("s_waitcnt vmcnt(0)" ::: "memory");
;     __syncthreads();
;     if (wave_s == 0 && lane_id_() == 0) {
;         unsigned* bar = b.bar;
;         __builtin_amdgcn_s_waitcnt(0);
;         unsigned nloc = b.st[0], nx = b.st[1];
;         if (nloc == 0u) { xcd_barrier_complete(bar, b.x, nloc, nx); b.st[0] = nloc; b.st[1] = nx; }
;         const unsigned old = xb_add(&bar[XB_XSUB(b.x)], 1u);
;         const unsigned gen = old / nloc;
;         if (old + 1u == (gen + 1u) * nloc) {
;             __builtin_amdgcn_fence(__ATOMIC_RELEASE, "agent");
;             asm volatile("s_waitcnt vmcnt(0)" ::: "memory");
;             const unsigned og = xb_add(&bar[XB_TOP], 1u);
;             const unsigned tg = og / nx;
;             if (og + 1u == (tg + 1u) * nx) xb_add(&bar[XB_TOPGEN], 1u);
;             else XB_SPIN(xb_ld(&bar[XB_TOPGEN]) == tg, bar);
;             __builtin_amdgcn_fence(__ATOMIC_ACQUIRE, "agent");
;             xb_add(&bar[XB_XGEN(b.x)], 1u);
;             asm volatile("s_waitcnt vmcnt(0)" ::: "memory");
;         } else {
;             XB_SPIN(xb_ld(&bar[XB_XGEN(b.x)]) == gen, bar);
;             __builtin_amdgcn_fence(__ATOMIC_ACQUIRE, "agent");
;             asm volatile("s_waitcnt vmcnt(0)" ::: "memory");
;         }
.Lla_S7:
	s_waitcnt vmcnt(0)
	v_readfirstlane_b32 s100, v5
	s_nop 3
	s_cmp_ge_u32 s100, 0x80
	s_cbranch_scc1 .Lcd_S7
	v_mov_b32_e32 v0, 0x5104
	s_mov_b32 s99, 0

; __device__ __forceinline__ int lane_id_() { int l; asm volatile("v_mbcnt_lo_u32_b32 %0, -1, 0\n\tv_mbcnt_hi_u32_b32 %0, -1, %0" : "=v"(l)); return l; }
; __device__ __forceinline__ unsigned xb_ld(unsigned* p)              { return __hip_atomic_load(p, __ATOMIC_RELAXED, __HIP_MEMORY_SCOPE_AGENT); }
; __device__ __forceinline__ unsigned xb_add(unsigned* p, unsigned v) { return __hip_atomic_fetch_add(p, v, __ATOMIC_RELAXED, __HIP_MEMORY_SCOPE_AGENT); }
; #define XB_SPIN(cond, bar) do { unsigned _sp = 0; while (cond) { __builtin_amdgcn_s_sleep(1); \
;     if ((++_sp & 255u) == 0u) { if (xb_ld(&(bar)[XB_TMO])) break; if (_sp > XB_SPIN_CAP) { atomicAdd(&(bar)[XB_TMO], 1u); break; } } } } while (0)
; __device__ __forceinline__ void xcd_barrier(const XcdBarrier& b, int wave_s) {
;     asm volatile("s_waitcnt vmcnt(0)" ::: "memory");
;     __syncthreads();
;     if (wave_s == 0 && lane_id_() == 0) {
;         unsigned* bar = b.bar;
;         __builtin_amdgcn_s_waitcnt(0);
;         unsigned nloc = b.st[0], nx = b.st[1];
;         if (nloc == 0u) { xcd_barrier_complete(bar, b.x, nloc, nx); b.st[0] = nloc; b.st[1] = nx; }
;         const unsigned old = xb_add(&bar[XB_XSUB(b.x)], 1u);
;         const unsigned gen = old / nloc;
;         if (old + 1u == (gen + 1u) * nloc) {
;             __builtin_amdgcn_fence(__ATOMIC_RELEASE, "agent");
;             asm volatile("s_waitcnt vmcnt(0)" ::: "memory");
;             const unsigned og = xb_add(&bar[XB_TOP], 1u);
;             const unsigned tg = og / nx;
;             if (og + 1u == (tg + 1u) * nx) xb_add(&bar[XB_TOPGEN], 1u);
;             else XB_SPIN(xb_ld(&bar[XB_TOPGEN]) == tg, bar);
;             __builtin_amdgcn_fence(__ATOMIC_ACQUIRE, "agent");
;             xb_add(&bar[XB_XGEN(b.x)], 1u);
;             asm volatile("s_waitcnt vmcnt(0)" ::: "memory");
;         } else {
;             XB_SPIN(xb_ld(&bar[XB_XGEN(b.x)]) == gen, bar);
;             __builtin_amdgcn_fence(__ATOMIC_ACQUIRE, "agent");
;             asm volatile("s_waitcnt vmcnt(0)" ::: "memory");
;         }
.LBB0_1589:
	s_waitcnt vmcnt(0)
	s_and_b64 vcc, exec, s[2:3]
	s_waitcnt vmcnt(0)
	s_barrier
	s_cbranch_vccnz .LBB0_1643
	v_mbcnt_lo_u32_b32 v0, -1, 0
	v_mbcnt_hi_u32_b32 v0, -1, v0
	s_nop 0
	v_cmp_eq_u32_e32 vcc, 0, v0
	s_and_saveexec_b64 s[8:9], vcc
	s_cbranch_execz .LBB0_1642
	s_cmp_eq_u32 s101, 1
	s_cbranch_scc0 .Lglob_S9
	s_cmpk_lt_u32 s33, 0x80
	s_cbranch_scc1 .Lnc_S9
	v_mov_b32_e32 v0, 0x5108
	v_mov_b32_e32 v1, 1
	global_atomic_add v0, v1, s[44:45]
.Lnc_S9:
	s_and_b32 s98, s33, 7
	s_lshl_b32 s99, s98, 2
	s_addk_i32 s99, 0x4800
	v_mov_b32_e32 v3, s99
	s_lshl_b32 s98, s98, 8
	s_addk_i32 s98, 0x4000
	v_mov_b32_e32 v0, s98
	v_mov_b32_e32 v1, 1
	global_atomic_add v2, v0, v1, s[44:45] sc0
	buffer_inv sc1
	s_waitcnt vmcnt(1)
	v_readfirstlane_b32 s98, v2
	s_nop 3
	s_add_u32 s99, s98, 1
	s_and_b32 s99, s99, 31
	s_lshr_b32 s98, s98, 5
	s_cmp_eq_u32 s99, 0
	s_cbranch_scc0 .Llw_S9
	global_atomic_add v3, v1, s[44:45]
	s_branch .Lla_S9

; __device__ __forceinline__ int lane_id_() { int l; asm volatile("v_mbcnt_lo_u32_b32 %0, -1, 0\n\tv_mbcnt_hi_u32_b32 %0, -1, %0" : "=v"(l)); return l; }
; __device__ __forceinline__ unsigned xb_ld(unsigned* p)              { return __hip_atomic_load(p, __ATOMIC_RELAXED, __HIP_MEMORY_SCOPE_AGENT); }
; __device__ __forceinline__ unsigned xb_add(unsigned* p, unsigned v) { return __hip_atomic_fetch_add(p, v, __ATOMIC_RELAXED, __HIP_MEMORY_SCOPE_AGENT); }
; #define XB_SPIN(cond, bar) do { unsigned _sp = 0; while (cond) { __builtin_amdgcn_s_sleep(1); \
;     if ((++_sp & 255u) == 0u) { if (xb_ld(&(bar)[XB_TMO])) break; if (_sp > XB_SPIN_CAP) { atomicAdd(&(bar)[XB_TMO], 1u); break; } } } } while (0)
; __device__ __forceinline__ void xcd_barrier(const XcdBarrier& b, int wave_s) {
;     asm volatile("s_waitcnt vmcnt(0)" ::: "memory");
;     __syncthreads();
;     if (wave_s == 0 && lane_id_() == 0) {
;         unsigned* bar = b.bar;
;         __builtin_amdgcn_s_waitcnt(0);
;         unsigned nloc = b.st[0], nx = b.st[1];
;         if (nloc == 0u) { xcd_barrier_complete(bar, b.x, nloc, nx); b.st[0] = nloc; b.st[1] = nx; }
;         const unsigned old = xb_add(&bar[XB_XSUB(b.x)], 1u);
;         const unsigned gen = old / nloc;
;         if (old + 1u == (gen + 1u) * nloc) {
;             __builtin_amdgcn_fence(__ATOMIC_RELEASE, "agent");
;             asm volatile("s_waitcnt vmcnt(0)" ::: "memory");
;             const unsigned og = xb_add(&bar[XB_TOP], 1u);
;             const unsigned tg = og / nx;
;             if (og + 1u == (tg + 1u) * nx) xb_add(&bar[XB_TOPGEN], 1u);
;             else XB_SPIN(xb_ld(&bar[XB_TOPGEN]) == tg, bar);
;             __builtin_amdgcn_fence(__ATOMIC_ACQUIRE, "agent");
;             xb_add(&bar[XB_XGEN(b.x)], 1u);
;             asm volatile("s_waitcnt vmcnt(0)" ::: "memory");
;         } else {
;             XB_SPIN(xb_ld(&bar[XB_XGEN(b.x)]) == gen, bar);
;             __builtin_amdgcn_fence(__ATOMIC_ACQUIRE, "agent");
;             asm volatile("s_waitcnt vmcnt(0)" ::: "memory");
;         }
.LBB0_1691:
	s_waitcnt vmcnt(0)
	s_and_b64 vcc, exec, s[2:3]
	s_waitcnt lgkmcnt(0)
	s_barrier
	s_cbranch_vccnz .LBB0_1745
	v_mbcnt_lo_u32_b32 v0, -1, 0
	v_mbcnt_hi_u32_b32 v0, -1, v0
	s_nop 0
	v_cmp_eq_u32_e32 vcc, 0, v0
	s_and_saveexec_b64 s[8:9], vcc
	s_cbranch_execz .LBB0_1744
	s_cmp_eq_u32 s101, 1
	s_cbranch_scc0 .Lglob_S10
	s_and_b32 s98, s33, 7
	s_lshl_b32 s99, s98, 2
	s_addk_i32 s99, 0x4800
	v_mov_b32_e32 v3, s99
	s_lshl_b32 s98, s98, 8
	s_addk_i32 s98, 0x4000
	v_mov_b32_e32 v0, s98
	v_mov_b32_e32 v1, 1
	global_atomic_add v2, v0, v1, s[44:45] sc0
	v_mov_b32_e32 v5, 0x5108
	global_load_dword v5, v5, s[44:45] sc1
	buffer_inv sc1
	s_waitcnt vmcnt(2)
	v_readfirstlane_b32 s98, v2
	s_nop 3
	s_add_u32 s99, s98, 1
	s_and_b32 s99, s99, 31
	s_lshr_b32 s98, s98, 5
	s_cmp_eq_u32 s99, 0
	s_cbranch_scc0 .Llw_S10
	global_atomic_add v3, v1, s[44:45]
	s_branch .Lla_S10

; __device__ __forceinline__ int lane_id_() { int l; asm volatile("v_mbcnt_lo_u32_b32 %0, -1, 0\n\tv_mbcnt_hi_u32_b32 %0, -1, %0" : "=v"(l)); return l; }
; __device__ __forceinline__ unsigned xb_ld(unsigned* p)              { return __hip_atomic_load(p, __ATOMIC_RELAXED, __HIP_MEMORY_SCOPE_AGENT); }
; __device__ __forceinline__ unsigned xb_add(unsigned* p, unsigned v) { return __hip_atomic_fetch_add(p, v, __ATOMIC_RELAXED, __HIP_MEMORY_SCOPE_AGENT); }
; #define XB_SPIN(cond, bar) do { unsigned _sp = 0; while (cond) { __builtin_amdgcn_s_sleep(1); \
;     if ((++_sp & 255u) == 0u) { if (xb_ld(&(bar)[XB_TMO])) break; if (_sp > XB_SPIN_CAP) { atomicAdd(&(bar)[XB_TMO], 1u); break; } } } } while (0)
; __device__ __forceinline__ void xcd_barrier(const XcdBarrier& b, int wave_s) {
;     asm volatile("s_waitcnt vmcnt(0)" ::: "memory");
;     __syncthreads();
;     if (wave_s == 0 && lane_id_() == 0) {
;         unsigned* bar = b.bar;
;         __builtin_amdgcn_s_waitcnt(0);
;         unsigned nloc = b.st[0], nx = b.st[1];
;         if (nloc == 0u) { xcd_barrier_complete(bar, b.x, nloc, nx); b.st[0] = nloc; b.st[1] = nx; }
;         const unsigned old = xb_add(&bar[XB_XSUB(b.x)], 1u);
;         const unsigned gen = old / nloc;
;         if (old + 1u == (gen + 1u) * nloc) {
;             __builtin_amdgcn_fence(__ATOMIC_RELEASE, "agent");
;             asm volatile("s_waitcnt vmcnt(0)" ::: "memory");
;             const unsigned og = xb_add(&bar[XB_TOP], 1u);
;             const unsigned tg = og / nx;
;             if (og + 1u == (tg + 1u) * nx) xb_add(&bar[XB_TOPGEN], 1u);
;             else XB_SPIN(xb_ld(&bar[XB_TOPGEN]) == tg, bar);
;             __builtin_amdgcn_fence(__ATOMIC_ACQUIRE, "agent");
;             xb_add(&bar[XB_XGEN(b.x)], 1u);
;             asm volatile("s_waitcnt vmcnt(0)" ::: "memory");
;         } else {
;             XB_SPIN(xb_ld(&bar[XB_XGEN(b.x)]) == gen, bar);
;             __builtin_amdgcn_fence(__ATOMIC_ACQUIRE, "agent");
;             asm volatile("s_waitcnt vmcnt(0)" ::: "memory");
;         }
.Lla_S10:
	s_waitcnt vmcnt(0)
	v_readfirstlane_b32 s100, v5
	s_nop 3
	s_cmp_ge_u32 s100, 0x80
	s_cbranch_scc1 .Lcd_S10
	v_mov_b32_e32 v0, 0x5108
	s_mov_b32 s99, 0

; #define PG8_WAIT_V8_STRICT() asm volatile("s_waitcnt vmcnt(8)" ::: "memory")
; template <class Epi, class Sched, bool ALIGN_EPI = false, bool SP2 = false>
; __device__ __forceinline__ void gemm_phase(PG8_LAS unsigned char* lds, const Gemm g, const Sched& S, const Epi& E, int wave_s) {
;     ...
;         for (int t = peeled ? 2 : 0; t < nt; t += 2) {
;             const bool last = (t == nt - 2);
;             const char* a1 = cA + (size_t)(t + 1) * kstep;
;             const char* a2 = last ? nA : cA + (size_t)(t + 2) * kstep; const char* b2 = last ? nB : cB + (size_t)(t + 2) * kstep;
;             const char* a3 = a2 + kstep; const char* b3 = b2 + kstep;
;             if (last && has_next) S.a_ready(nxt);
;             if constexpr (SP2) {
;             PG8_SP2_PAIR(PG8_WAIT_V8_STRICT);
.Lwsb_2:
	v_add_u32_e32 v151, s74, v146
	v_add_u32_e32 v150, s75, v146
	ds_read_b128 v[152:155], v151
	ds_read_b128 v[156:159], v151 offset:1024
	ds_read_b128 v[160:163], v151 offset:2048
	ds_read_b128 v[164:167], v151 offset:3072
	ds_read_b128 v[168:171], v150
	ds_read_b128 v[172:175], v150 offset:1024
	ds_read_b128 v[176:179], v150 offset:2048
	ds_read_b128 v[180:183], v150 offset:3072
	s_add_u32 s10, s56, 0x100
	s_addc_u32 s11, s57, 0
	s_cmp_eq_u32 s88, 12
	s_cselect_b32 s54, s61, s10
	s_cselect_b32 s55, s60, s11
	s_cselect_b32 s42, s87, s6
	s_cselect_b32 s43, s82, s7
	s_add_u32 s40, s54, 0x80
	s_addc_u32 s41, s55, 0
	s_add_u32 s56, s56, 0x40080
	s_addc_u32 s57, s57, 0
	s_add_i32 s85, s37, 0xc000
	ds_read_b128 v[184:187], v149
	ds_read_b128 v[188:191], v149 offset:1024
	ds_read_b128 v[192:195], v149 offset:2048
	ds_read_b128 v[196:199], v149 offset:3072
	ds_read_b128 v[200:203], v149 offset:4096
	ds_read_b128 v[204:207], v149 offset:5120
	ds_read_b128 v[208:211], v149 offset:6144
	ds_read_b128 v[212:215], v149 offset:7168
	s_mov_b32 m0, s85
	s_add_i32 s12, s37, 0xe000
	global_load_lds_dwordx4 v132, s[56:57]
	s_mov_b32 m0, s12
	s_nop 0
	global_load_lds_dwordx4 v136, s[56:57]
	s_waitcnt vmcnt(8)
	s_waitcnt lgkmcnt(0)
	s_barrier
	s_waitcnt lgkmcnt(0)
	v_mfma_f32_16x16x32_bf16 v[128:131], v[152:155], v[184:187], v[128:131]
	v_mfma_f32_16x16x32_bf16 v[124:127], v[160:163], v[184:187], v[124:127]
	v_mfma_f32_16x16x32_bf16 v[112:115], v[152:155], v[192:195], v[112:115]
	v_mfma_f32_16x16x32_bf16 v[108:111], v[160:163], v[192:195], v[108:111]
	v_mfma_f32_16x16x32_bf16 v[96:99], v[152:155], v[200:203], v[96:99]
	v_mfma_f32_16x16x32_bf16 v[92:95], v[160:163], v[200:203], v[92:95]
	v_mfma_f32_16x16x32_bf16 v[80:83], v[152:155], v[208:211], v[80:83]
	v_mfma_f32_16x16x32_bf16 v[76:79], v[160:163], v[208:211], v[76:79]
	v_mfma_f32_16x16x32_bf16 v[128:131], v[156:159], v[188:191], v[128:131]
	v_mfma_f32_16x16x32_bf16 v[124:127], v[164:167], v[188:191], v[124:127]
	v_mfma_f32_16x16x32_bf16 v[112:115], v[156:159], v[196:199], v[112:115]
	v_mfma_f32_16x16x32_bf16 v[108:111], v[164:167], v[196:199], v[108:111]
	v_mfma_f32_16x16x32_bf16 v[96:99], v[156:159], v[204:207], v[96:99]
	v_mfma_f32_16x16x32_bf16 v[92:95], v[164:167], v[204:207], v[92:95]
	v_mfma_f32_16x16x32_bf16 v[80:83], v[156:159], v[212:215], v[80:83]
	v_mfma_f32_16x16x32_bf16 v[76:79], v[164:167], v[212:215], v[76:79]
	v_mfma_f32_16x16x32_bf16 v[120:123], v[168:171], v[184:187], v[120:123]
	v_mfma_f32_16x16x32_bf16 v[116:119], v[176:179], v[184:187], v[116:119]
	v_mfma_f32_16x16x32_bf16 v[104:107], v[168:171], v[192:195], v[104:107]
	v_mfma_f32_16x16x32_bf16 v[100:103], v[176:179], v[192:195], v[100:103]
	v_mfma_f32_16x16x32_bf16 v[88:91], v[168:171], v[200:203], v[88:91]
	v_mfma_f32_16x16x32_bf16 v[84:87], v[176:179], v[200:203], v[84:87]
	v_mfma_f32_16x16x32_bf16 v[72:75], v[168:171], v[208:211], v[72:75]
	v_mfma_f32_16x16x32_bf16 v[68:71], v[176:179], v[208:211], v[68:71]
	v_mfma_f32_16x16x32_bf16 v[120:123], v[172:175], v[188:191], v[120:123]
	v_mfma_f32_16x16x32_bf16 v[116:119], v[180:183], v[188:191], v[116:119]
	v_mfma_f32_16x16x32_bf16 v[104:107], v[172:175], v[196:199], v[104:107]
	v_mfma_f32_16x16x32_bf16 v[100:103], v[180:183], v[196:199], v[100:103]
	v_mfma_f32_16x16x32_bf16 v[88:91], v[172:175], v[204:207], v[88:91]
	v_mfma_f32_16x16x32_bf16 v[84:87], v[180:183], v[204:207], v[84:87]
	v_mfma_f32_16x16x32_bf16 v[72:75], v[172:175], v[212:215], v[72:75]
	v_mfma_f32_16x16x32_bf16 v[68:71], v[180:183], v[212:215], v[68:71]
	s_barrier
	s_setprio 1
	s_mov_b64 s[56:57], s[42:43]
	s_add_i32 s79, s74, s64
	ds_read_b128 v[184:187], v149 offset:16384
	ds_read_b128 v[188:191], v149 offset:17408
	ds_read_b128 v[192:195], v149 offset:18432
	ds_read_b128 v[196:199], v149 offset:19456
	ds_read_b128 v[200:203], v149 offset:20480
	ds_read_b128 v[204:207], v149 offset:21504
	ds_read_b128 v[208:211], v149 offset:22528
	ds_read_b128 v[212:215], v149 offset:23552
	s_mov_b32 m0, s79
	s_add_i32 s27, s79, 0x2000
	global_load_lds_dwordx4 v134, s[56:57]
	s_mov_b64 s[98:99], s[56:57]
	s_add_u32 s56, s42, 0x40000
	s_mov_b32 m0, s27
	s_addc_u32 s57, s43, 0
	s_add_i32 s29, s75, s64
	global_load_lds_dwordx4 v138, s[98:99]
	s_mov_b32 m0, s29
	s_add_i32 s77, s29, 0x2000
	global_load_lds_dwordx4 v134, s[56:57]
	s_mov_b64 s[98:99], s[56:57]
	s_mov_b32 m0, s77
	s_mov_b64 s[56:57], s[54:55]
	global_load_lds_dwordx4 v138, s[98:99]
	s_mov_b32 m0, s37
	s_nop 0
	global_load_lds_dwordx4 v132, s[56:57]
	s_mov_b32 m0, s39
	s_nop 0
	global_load_lds_dwordx4 v136, s[56:57]
	s_setprio 0
	s_waitcnt vmcnt(8)
	s_waitcnt lgkmcnt(0)
	s_barrier
	s_waitcnt lgkmcnt(0)
	v_mfma_f32_16x16x32_bf16 v[64:67], v[152:155], v[184:187], v[64:67]
	v_mfma_f32_16x16x32_bf16 v[60:63], v[160:163], v[184:187], v[60:63]
	v_mfma_f32_16x16x32_bf16 v[48:51], v[152:155], v[192:195], v[48:51]
	v_mfma_f32_16x16x32_bf16 v[44:47], v[160:163], v[192:195], v[44:47]
	v_mfma_f32_16x16x32_bf16 v[32:35], v[152:155], v[200:203], v[32:35]
	v_mfma_f32_16x16x32_bf16 v[28:31], v[160:163], v[200:203], v[28:31]
	v_mfma_f32_16x16x32_bf16 v[16:19], v[152:155], v[208:211], v[16:19]
	v_mfma_f32_16x16x32_bf16 v[12:15], v[160:163], v[208:211], v[12:15]
	v_mfma_f32_16x16x32_bf16 v[64:67], v[156:159], v[188:191], v[64:67]
	v_mfma_f32_16x16x32_bf16 v[60:63], v[164:167], v[188:191], v[60:63]
	v_mfma_f32_16x16x32_bf16 v[48:51], v[156:159], v[196:199], v[48:51]
	v_mfma_f32_16x16x32_bf16 v[44:47], v[164:167], v[196:199], v[44:47]
	v_mfma_f32_16x16x32_bf16 v[32:35], v[156:159], v[204:207], v[32:35]
	v_mfma_f32_16x16x32_bf16 v[28:31], v[164:167], v[204:207], v[28:31]
	v_mfma_f32_16x16x32_bf16 v[16:19], v[156:159], v[212:215], v[16:19]
	v_mfma_f32_16x16x32_bf16 v[12:15], v[164:167], v[212:215], v[12:15]
	v_mfma_f32_16x16x32_bf16 v[56:59], v[168:171], v[184:187], v[56:59]
	v_mfma_f32_16x16x32_bf16 v[52:55], v[176:179], v[184:187], v[52:55]
	v_mfma_f32_16x16x32_bf16 v[40:43], v[168:171], v[192:195], v[40:43]
	v_mfma_f32_16x16x32_bf16 v[36:39], v[176:179], v[192:195], v[36:39]
	v_mfma_f32_16x16x32_bf16 v[24:27], v[168:171], v[200:203], v[24:27]
	v_mfma_f32_16x16x32_bf16 v[20:23], v[176:179], v[200:203], v[20:23]
	v_mfma_f32_16x16x32_bf16 v[8:11], v[168:171], v[208:211], v[8:11]
	v_mfma_f32_16x16x32_bf16 v[2:5], v[176:179], v[208:211], v[4:7]
	v_mfma_f32_16x16x32_bf16 v[56:59], v[172:175], v[188:191], v[56:59]
	v_mfma_f32_16x16x32_bf16 v[52:55], v[180:183], v[188:191], v[52:55]
	v_mfma_f32_16x16x32_bf16 v[40:43], v[172:175], v[196:199], v[40:43]
	v_mfma_f32_16x16x32_bf16 v[36:39], v[180:183], v[196:199], v[36:39]
	v_mfma_f32_16x16x32_bf16 v[24:27], v[172:175], v[204:207], v[24:27]
	v_mfma_f32_16x16x32_bf16 v[20:23], v[180:183], v[204:207], v[20:23]
	v_mfma_f32_16x16x32_bf16 v[8:11], v[172:175], v[212:215], v[8:11]
	v_mfma_f32_16x16x32_bf16 v[2:5], v[180:183], v[212:215], v[2:5]
	s_barrier
	s_add_i32 s86, 0, 0x18000
	s_add_i32 s56, 0, 0x1c000
	v_add_u32_e32 v152, s86, v146
	v_add_u32_e32 v153, s56, v146
	ds_read_b128 v[154:157], v152
	ds_read_b128 v[158:161], v152 offset:1024
	ds_read_b128 v[162:165], v152 offset:2048
	ds_read_b128 v[166:169], v152 offset:3072
	ds_read_b128 v[170:173], v153
	ds_read_b128 v[174:177], v153 offset:1024
	ds_read_b128 v[178:181], v153 offset:2048
	ds_read_b128 v[182:185], v153 offset:3072
	s_add_u32 s54, s54, 0x40000
	s_addc_u32 s55, s55, 0
	s_mov_b32 m0, s66
	ds_read_b128 v[186:189], v149 offset:32768
	ds_read_b128 v[190:193], v149 offset:33792
	ds_read_b128 v[194:197], v149 offset:34816
	ds_read_b128 v[198:201], v149 offset:35840
	ds_read_b128 v[202:205], v149 offset:36864
	ds_read_b128 v[206:209], v149 offset:37888
	ds_read_b128 v[210:213], v149 offset:38912
	ds_read_b128 v[214:217], v149 offset:39936
	s_nop 0
	global_load_lds_dwordx4 v132, s[54:55]
	s_mov_b32 m0, s67
	s_nop 0
	global_load_lds_dwordx4 v136, s[54:55]
	s_waitcnt vmcnt(8)
	s_waitcnt lgkmcnt(0)
	s_barrier
	s_waitcnt lgkmcnt(0)
	v_mfma_f32_16x16x32_bf16 v[128:131], v[154:157], v[186:189], v[128:131]
	v_mfma_f32_16x16x32_bf16 v[124:127], v[162:165], v[186:189], v[124:127]
	v_mfma_f32_16x16x32_bf16 v[112:115], v[154:157], v[194:197], v[112:115]
	v_mfma_f32_16x16x32_bf16 v[108:111], v[162:165], v[194:197], v[108:111]
	v_mfma_f32_16x16x32_bf16 v[96:99], v[154:157], v[202:205], v[96:99]
	v_mfma_f32_16x16x32_bf16 v[92:95], v[162:165], v[202:205], v[92:95]
	v_mfma_f32_16x16x32_bf16 v[80:83], v[154:157], v[210:213], v[80:83]
	v_mfma_f32_16x16x32_bf16 v[76:79], v[162:165], v[210:213], v[76:79]
	v_mfma_f32_16x16x32_bf16 v[128:131], v[158:161], v[190:193], v[128:131]
	v_mfma_f32_16x16x32_bf16 v[124:127], v[166:169], v[190:193], v[124:127]
	v_mfma_f32_16x16x32_bf16 v[112:115], v[158:161], v[198:201], v[112:115]
	v_mfma_f32_16x16x32_bf16 v[108:111], v[166:169], v[198:201], v[108:111]
	v_mfma_f32_16x16x32_bf16 v[96:99], v[158:161], v[206:209], v[96:99]
	v_mfma_f32_16x16x32_bf16 v[92:95], v[166:169], v[206:209], v[92:95]
	v_mfma_f32_16x16x32_bf16 v[80:83], v[158:161], v[214:217], v[80:83]
	v_mfma_f32_16x16x32_bf16 v[76:79], v[166:169], v[214:217], v[76:79]
	v_mfma_f32_16x16x32_bf16 v[120:123], v[170:173], v[186:189], v[120:123]
	v_mfma_f32_16x16x32_bf16 v[116:119], v[178:181], v[186:189], v[116:119]
	v_mfma_f32_16x16x32_bf16 v[104:107], v[170:173], v[194:197], v[104:107]
	v_mfma_f32_16x16x32_bf16 v[100:103], v[178:181], v[194:197], v[100:103]
	v_mfma_f32_16x16x32_bf16 v[88:91], v[170:173], v[202:205], v[88:91]
	v_mfma_f32_16x16x32_bf16 v[84:87], v[178:181], v[202:205], v[84:87]
	v_mfma_f32_16x16x32_bf16 v[72:75], v[170:173], v[210:213], v[72:75]
	v_mfma_f32_16x16x32_bf16 v[68:71], v[178:181], v[210:213], v[68:71]
	v_mfma_f32_16x16x32_bf16 v[120:123], v[174:177], v[190:193], v[120:123]
	v_mfma_f32_16x16x32_bf16 v[116:119], v[182:185], v[190:193], v[116:119]
	v_mfma_f32_16x16x32_bf16 v[104:107], v[174:177], v[198:201], v[104:107]
	v_mfma_f32_16x16x32_bf16 v[100:103], v[182:185], v[198:201], v[100:103]
	v_mfma_f32_16x16x32_bf16 v[88:91], v[174:177], v[206:209], v[88:91]
	v_mfma_f32_16x16x32_bf16 v[84:87], v[182:185], v[206:209], v[84:87]
	v_mfma_f32_16x16x32_bf16 v[72:75], v[174:177], v[214:217], v[72:75]
	v_mfma_f32_16x16x32_bf16 v[68:71], v[182:185], v[214:217], v[68:71]
	s_barrier
; #define PG8_LAS __attribute__((address_space(3)))
; __device__ __forceinline__ float fast_sigmoid(float v) { return __builtin_amdgcn_rcpf(1.0f + __builtin_amdgcn_exp2f(-1.44269504089f * v)); }
;     __device__ __forceinline__ void operator()(const f32x4 (&acc)[2][2][4][2], const Unit& u, int wr, int wc, int fr, int fq, PG8_LAS unsigned char* lds, int wid) const {
;     ...
;                 const float rstd = __builtin_amdgcn_rsqf(*(const PG8_LAS float*)(lds + PRE_SLOT + wid * 512 + (m & 1) * 256 + (fr + 16 * ((ai * 4 + m) >> 1)) * 4) * (1.0f / 1024.0f) + 1e-6f);
; #pragma unroll
;                 for (int bj = 0; bj < 2; ++bj) {
;                     float h[8];
; #pragma unroll
;                     for (int n = 0; n < 2; ++n)
; #pragma unroll
;                         for (int j = 0; j < 4; ++j) { float v = acc[ai][bj][m][n][j] * rstd;
;                             if (act) { const float z = 1.5957691216f * (v + 0.044715f * v * v * v); v = v * fast_sigmoid(z); }
	s_setprio 1
	s_add_u32 s54, s42, 0x80
	s_addc_u32 s55, s43, 0
	s_add_i32 s86, s86, s64
	ds_read_b128 v[186:189], v149 offset:49152
	ds_read_b128 v[190:193], v149 offset:50176
	ds_read_b128 v[194:197], v149 offset:51200
	ds_read_b128 v[198:201], v149 offset:52224
	ds_read_b128 v[202:205], v149 offset:53248
	ds_read_b128 v[206:209], v149 offset:54272
	ds_read_b128 v[210:213], v149 offset:55296
	ds_read_b128 v[214:217], v149 offset:56320
	s_mov_b32 m0, s86
	s_nop 0
	global_load_lds_dwordx4 v134, s[54:55]
	s_mov_b64 s[98:99], s[54:55]
	s_add_i32 s54, s86, 0x2000
	s_add_u32 s42, s42, 0x40080
	s_mov_b32 m0, s54
	s_addc_u32 s43, s43, 0
	s_add_i32 s55, s56, s64
	global_load_lds_dwordx4 v138, s[98:99]
	s_mov_b32 m0, s55
	s_add_i32 s78, s55, 0x2000
	global_load_lds_dwordx4 v134, s[42:43]
	s_mov_b32 m0, s78
	s_nop 0
	global_load_lds_dwordx4 v138, s[42:43]
	s_mov_b32 m0, s68
	s_nop 0
	global_load_lds_dwordx4 v132, s[40:41]
	s_mov_b32 m0, s69
	s_nop 0
	global_load_lds_dwordx4 v136, s[40:41]
	s_setprio 0
	s_waitcnt vmcnt(8)
	s_waitcnt lgkmcnt(0)
	s_barrier
	s_waitcnt lgkmcnt(0)
	v_mfma_f32_16x16x32_bf16 v[64:67], v[154:157], v[186:189], v[64:67]
	v_mfma_f32_16x16x32_bf16 v[60:63], v[162:165], v[186:189], v[60:63]
	v_mfma_f32_16x16x32_bf16 v[48:51], v[154:157], v[194:197], v[48:51]
	v_mfma_f32_16x16x32_bf16 v[44:47], v[162:165], v[194:197], v[44:47]
	v_mfma_f32_16x16x32_bf16 v[32:35], v[154:157], v[202:205], v[32:35]
	v_mfma_f32_16x16x32_bf16 v[28:31], v[162:165], v[202:205], v[28:31]
	v_mfma_f32_16x16x32_bf16 v[16:19], v[154:157], v[210:213], v[16:19]
	v_mfma_f32_16x16x32_bf16 v[12:15], v[162:165], v[210:213], v[12:15]
	v_mfma_f32_16x16x32_bf16 v[64:67], v[158:161], v[190:193], v[64:67]
	v_mfma_f32_16x16x32_bf16 v[60:63], v[166:169], v[190:193], v[60:63]
	v_mfma_f32_16x16x32_bf16 v[48:51], v[158:161], v[198:201], v[48:51]
	v_mfma_f32_16x16x32_bf16 v[44:47], v[166:169], v[198:201], v[44:47]
	v_mfma_f32_16x16x32_bf16 v[32:35], v[158:161], v[206:209], v[32:35]
	v_mfma_f32_16x16x32_bf16 v[28:31], v[166:169], v[206:209], v[28:31]
	v_mfma_f32_16x16x32_bf16 v[16:19], v[158:161], v[214:217], v[16:19]
	v_mfma_f32_16x16x32_bf16 v[12:15], v[166:169], v[214:217], v[12:15]
	v_mfma_f32_16x16x32_bf16 v[56:59], v[170:173], v[186:189], v[56:59]
	v_mfma_f32_16x16x32_bf16 v[52:55], v[178:181], v[186:189], v[52:55]
	v_mfma_f32_16x16x32_bf16 v[40:43], v[170:173], v[194:197], v[40:43]
	v_mfma_f32_16x16x32_bf16 v[36:39], v[178:181], v[194:197], v[36:39]
	v_mfma_f32_16x16x32_bf16 v[24:27], v[170:173], v[202:205], v[24:27]
	v_mfma_f32_16x16x32_bf16 v[20:23], v[178:181], v[202:205], v[20:23]
	v_mfma_f32_16x16x32_bf16 v[6:9], v[170:173], v[210:213], v[8:11]
	v_mfma_f32_16x16x32_bf16 v[2:5], v[178:181], v[210:213], v[2:5]
	v_mfma_f32_16x16x32_bf16 v[56:59], v[174:177], v[190:193], v[56:59]
	v_mfma_f32_16x16x32_bf16 v[52:55], v[182:185], v[190:193], v[52:55]
	v_mfma_f32_16x16x32_bf16 v[40:43], v[174:177], v[198:201], v[40:43]
	v_mfma_f32_16x16x32_bf16 v[36:39], v[182:185], v[198:201], v[36:39]
	v_mfma_f32_16x16x32_bf16 v[24:27], v[174:177], v[206:209], v[24:27]
	v_mfma_f32_16x16x32_bf16 v[20:23], v[182:185], v[206:209], v[20:23]
	v_mfma_f32_16x16x32_bf16 v[8:11], v[174:177], v[214:217], v[6:9]
	v_mfma_f32_16x16x32_bf16 v[4:7], v[182:185], v[214:217], v[2:5]
	s_barrier
	s_add_i32 s88, s88, 2
	s_add_u32 s6, s6, 0x100
	s_addc_u32 s7, s7, 0
	s_cmp_gt_u32 s88, 13
	s_mov_b64 s[56:57], s[10:11]
	s_cbranch_scc0 .LBB0_1764
	s_and_b64 vcc, exec, s[18:19]
	s_cbranch_vccz .LBB0_1767
	s_cmp_eq_u32 s101, 1
	s_cbranch_scc0 .Lwok_2
	v_mbcnt_lo_u32_b32 v188, -1, 0
	v_mbcnt_hi_u32_b32 v188, -1, v188
	v_lshlrev_b32_e32 v188, 2, v188
	v_add_u32_e32 v189, 0x23400, v188
	ds_read_b32 v189, v189
	s_waitcnt lgkmcnt(0)
	v_cmp_gt_u32_e32 vcc, 10, v189
	s_nop 3
	s_and_b32 vcc_lo, vcc_lo, 0xff
	s_cmp_eq_u32 vcc_lo, 0
	s_cbranch_scc1 .Lwok_2
	s_mov_b32 s100, 0
.Lwsl_2:
	v_add_u32_e32 v189, 0x4800, v188
	global_load_dword v189, v189, s[44:45] sc1
	s_waitcnt vmcnt(0)
	v_cmp_gt_u32_e32 vcc, 10, v189
	s_nop 3
	s_and_b32 vcc_lo, vcc_lo, 0xff
	s_cmp_eq_u32 vcc_lo, 0
	s_cbranch_scc1 .Lwok_2
	s_add_u32 s100, s100, 1
	s_cmp_lt_u32 s100, 0x4000
	s_cbranch_scc1 .Lwsl_2
.Lwok_2:
	s_barrier
.LBB0_1767:
	v_add_u32_e32 v154, s65, v145
	ds_read_b32 v0, v154
	s_ashr_i32 s40, s38, 2
	s_cmp_gt_i32 s40, 0
	s_cselect_b64 s[42:43], -1, 0
	s_cmp_lt_i32 s40, 1
	s_waitcnt lgkmcnt(0)
	v_fmamk_f32 v0, v0, 0x3a800000, v148
	v_rsq_f32_e32 v155, v0
	s_nop 0
	v_mul_f32_e32 v128, v128, v155
	s_cbranch_scc1 .LBB0_1769
	v_mul_f32_e32 v0, 0x3d372713, v128
	v_mul_f32_e32 v0, v128, v0
	v_fma_f32 v0, v128, v0, v128
	v_mul_f32_e32 v0, 0x3fcc422a, v0
	v_mul_f32_e32 v0, 0xbfb8aa3b, v0
	v_exp_f32_e32 v0, v0
	s_nop 0
	v_add_f32_e32 v0, 1.0, v0
	v_rcp_f32_e32 v0, v0
	s_nop 0
	v_mul_f32_e32 v128, v128, v0

; __device__ __forceinline__ unsigned pk_bf16(float lo, float hi) { typedef __bf16 b2_t __attribute__((ext_vector_type(2))); f32x2 v = {lo, hi}; b2_t b = __builtin_convertvector(v, b2_t); return __builtin_bit_cast(unsigned, b); }
; #define PG8_BAR __builtin_amdgcn_s_barrier()
;     __device__ __forceinline__ void operator()(const f32x4 (&acc)[2][2][4][2], const Unit& u, int wr, int wc, int fr, int fq, PG8_LAS unsigned char* lds, int wid) const {
;     ...
;                     u32x4 w; w.x = pk_bf16(h[0], h[1]); w.y = pk_bf16(h[2], h[3]); w.z = pk_bf16(h[4], h[5]); w.w = pk_bf16(h[6], h[7]);
;                     *(u32x4*)(basep + (size_t)(row0 + ai * HALF + m * 16) * 1024 + col0 + bj * HALF) = w;
; template <class Epi, class Sched, bool ALIGN_EPI = false, bool SP2 = false>
; __device__ __forceinline__ void gemm_phase(PG8_LAS unsigned char* lds, const Gemm g, const Sched& S, const Epi& E, int wave_s) {
;     ...
;         if (!has_next) break;
; #pragma unroll
;         for (int a = 0; a < 2; ++a)
; #pragma unroll
;             for (int b = 0; b < 2; ++b)
; #pragma unroll
;                 for (int m = 0; m < 4; ++m)
; #pragma unroll
;                     for (int n = 0; n < 2; ++n) acc[a][b][m][n] = (f32x4){0.f, 0.f, 0.f, 0.f};
;         cur = nxt; cA = nA; cB = nB; ++ui;
;         if constexpr (ALIGN_EPI) { if (wr == 1) PG8_BAR; }
;         if constexpr (Epi::NPRE > 0) E.prefetch(lds, wid, cur, wr, fr, fq);
.LBB0_2023:
	v_lshl_add_u64 v[12:13], v[2:3], 0, s[24:25]
	v_cvt_pk_bf16_f32 v2, v8, v9
	v_cvt_pk_bf16_f32 v3, v10, v11
	v_cvt_pk_bf16_f32 v4, v4, v5
	v_cvt_pk_bf16_f32 v5, v6, v0
	s_andn2_b64 vcc, exec, s[8:9]
	s_mov_b64 s[8:9], -1
	global_store_dwordx4 v[12:13], v[2:5], off offset:256 sc1
	s_cbranch_vccnz .LBB0_1756
	s_andn2_b64 vcc, exec, s[16:17]
	s_cbranch_vccnz .LBB0_1755
	s_barrier
	s_branch .LBB0_1755
.Lws_2:
	v_mbcnt_lo_u32_b32 v152, -1, 0
	v_mbcnt_hi_u32_b32 v152, -1, v152
	v_lshlrev_b32_e32 v152, 2, v152
	v_add_u32_e32 v152, 0x4800, v152
	s_mov_b32 m0, 0x23400
	s_nop 0
	global_load_lds_dword v152, s[44:45] sc1
	s_branch .Lwsb_2

; template <class Epi, class Sched, bool ALIGN_EPI = false, bool SP2 = false>
; __device__ __forceinline__ void gemm_phase(PG8_LAS unsigned char* lds, const Gemm g, const Sched& S, const Epi& E, int wave_s) {
;     ...
;         const char* nA = has_next ? (const char*)g.A + (size_t)nxt.pm * tstep : cA; const char* nB = has_next ? (const char*)g.Bt + (size_t)nxt.pn * tstep : cB;
;         for (int t = peeled ? 2 : 0; t < nt; t += 2) {
;             const bool last = (t == nt - 2);
;             const char* a1 = cA + (size_t)(t + 1) * kstep;
;             const char* a2 = last ? nA : cA + (size_t)(t + 2) * kstep; const char* b2 = last ? nB : cB + (size_t)(t + 2) * kstep;
;             const char* a3 = a2 + kstep; const char* b3 = b2 + kstep;
.Lwsb_3:
	v_add_u32_e32 v151, s59, v146
	v_add_u32_e32 v150, s60, v146
	ds_read_b128 v[152:155], v151
	ds_read_b128 v[156:159], v151 offset:1024
	ds_read_b128 v[160:163], v151 offset:2048
	ds_read_b128 v[164:167], v151 offset:3072
	ds_read_b128 v[168:171], v150
	ds_read_b128 v[172:175], v150 offset:1024
	ds_read_b128 v[176:179], v150 offset:2048
	ds_read_b128 v[180:183], v150 offset:3072
	s_add_u32 s24, s34, 0x100
	s_addc_u32 s25, s35, 0
	s_cmp_eq_u32 s70, 12
	s_cselect_b32 s30, s67, s24
	s_cselect_b32 s31, s66, s25
	s_cselect_b32 s28, s69, s71
	s_cselect_b32 s29, s68, s72
	s_add_u32 s26, s30, 0x80
	s_addc_u32 s27, s31, 0
	s_add_u32 s34, s34, 0x40080
	s_addc_u32 s35, s35, 0
	s_add_i32 s65, s42, 0xc000
	ds_read_b128 v[184:187], v149
	ds_read_b128 v[188:191], v149 offset:1024
	ds_read_b128 v[192:195], v149 offset:2048
	ds_read_b128 v[196:199], v149 offset:3072
	ds_read_b128 v[200:203], v149 offset:4096
	ds_read_b128 v[204:207], v149 offset:5120
	ds_read_b128 v[208:211], v149 offset:6144
	ds_read_b128 v[212:215], v149 offset:7168
	s_mov_b32 m0, s65
	s_add_i32 s8, s42, 0xe000
	global_load_lds_dwordx4 v138, s[34:35]
	s_mov_b32 m0, s8
	s_nop 0
	global_load_lds_dwordx4 v134, s[34:35]
	s_waitcnt vmcnt(8)
	s_waitcnt lgkmcnt(0)
	s_barrier
	s_waitcnt lgkmcnt(0)
	v_mfma_f32_16x16x32_bf16 v[124:127], v[152:155], v[184:187], v[124:127]
	v_mfma_f32_16x16x32_bf16 v[116:119], v[160:163], v[184:187], v[116:119]
	v_mfma_f32_16x16x32_bf16 v[108:111], v[152:155], v[192:195], v[108:111]
	v_mfma_f32_16x16x32_bf16 v[100:103], v[160:163], v[192:195], v[100:103]
	v_mfma_f32_16x16x32_bf16 v[92:95], v[152:155], v[200:203], v[92:95]
	v_mfma_f32_16x16x32_bf16 v[84:87], v[160:163], v[200:203], v[84:87]
	v_mfma_f32_16x16x32_bf16 v[76:79], v[152:155], v[208:211], v[76:79]
	v_mfma_f32_16x16x32_bf16 v[60:63], v[160:163], v[208:211], v[60:63]
	v_mfma_f32_16x16x32_bf16 v[124:127], v[156:159], v[188:191], v[124:127]
	v_mfma_f32_16x16x32_bf16 v[116:119], v[164:167], v[188:191], v[116:119]
	v_mfma_f32_16x16x32_bf16 v[108:111], v[156:159], v[196:199], v[108:111]
	v_mfma_f32_16x16x32_bf16 v[100:103], v[164:167], v[196:199], v[100:103]
	v_mfma_f32_16x16x32_bf16 v[92:95], v[156:159], v[204:207], v[92:95]
	v_mfma_f32_16x16x32_bf16 v[84:87], v[164:167], v[204:207], v[84:87]
	v_mfma_f32_16x16x32_bf16 v[76:79], v[156:159], v[212:215], v[76:79]
	v_mfma_f32_16x16x32_bf16 v[60:63], v[164:167], v[212:215], v[60:63]
	v_mfma_f32_16x16x32_bf16 v[128:131], v[168:171], v[184:187], v[128:131]
	v_mfma_f32_16x16x32_bf16 v[120:123], v[176:179], v[184:187], v[120:123]
	v_mfma_f32_16x16x32_bf16 v[112:115], v[168:171], v[192:195], v[112:115]
	v_mfma_f32_16x16x32_bf16 v[104:107], v[176:179], v[192:195], v[104:107]
	v_mfma_f32_16x16x32_bf16 v[96:99], v[168:171], v[200:203], v[96:99]
	v_mfma_f32_16x16x32_bf16 v[88:91], v[176:179], v[200:203], v[88:91]
	v_mfma_f32_16x16x32_bf16 v[80:83], v[168:171], v[208:211], v[80:83]
	v_mfma_f32_16x16x32_bf16 v[68:71], v[176:179], v[208:211], v[68:71]
	v_mfma_f32_16x16x32_bf16 v[128:131], v[172:175], v[188:191], v[128:131]
	v_mfma_f32_16x16x32_bf16 v[120:123], v[180:183], v[188:191], v[120:123]
	v_mfma_f32_16x16x32_bf16 v[112:115], v[172:175], v[196:199], v[112:115]
	v_mfma_f32_16x16x32_bf16 v[104:107], v[180:183], v[196:199], v[104:107]
	v_mfma_f32_16x16x32_bf16 v[96:99], v[172:175], v[204:207], v[96:99]
	v_mfma_f32_16x16x32_bf16 v[88:91], v[180:183], v[204:207], v[88:91]
	v_mfma_f32_16x16x32_bf16 v[80:83], v[172:175], v[212:215], v[80:83]
	v_mfma_f32_16x16x32_bf16 v[68:71], v[180:183], v[212:215], v[68:71]
	s_barrier
	s_setprio 1
	s_mov_b64 s[34:35], s[28:29]
	s_add_i32 s64, s59, s38
	ds_read_b128 v[184:187], v149 offset:16384
	ds_read_b128 v[188:191], v149 offset:17408
	ds_read_b128 v[192:195], v149 offset:18432
	ds_read_b128 v[196:199], v149 offset:19456
	ds_read_b128 v[200:203], v149 offset:20480
	ds_read_b128 v[204:207], v149 offset:21504
	ds_read_b128 v[208:211], v149 offset:22528
	ds_read_b128 v[212:215], v149 offset:23552
	s_mov_b32 m0, s64
	s_add_i32 s15, s64, 0x2000
	global_load_lds_dwordx4 v136, s[34:35]
	s_mov_b64 s[98:99], s[34:35]
	s_add_u32 s34, s28, 0x40000
	s_mov_b32 m0, s15
	s_addc_u32 s35, s29, 0
	s_add_i32 s17, s60, s38
	global_load_lds_dwordx4 v132, s[98:99]
	s_mov_b32 m0, s17
	s_add_i32 s63, s17, 0x2000
	global_load_lds_dwordx4 v136, s[34:35]
	s_mov_b64 s[98:99], s[34:35]
	s_mov_b32 m0, s63
	s_mov_b64 s[34:35], s[30:31]
	global_load_lds_dwordx4 v132, s[98:99]
	s_mov_b32 m0, s42
	s_nop 0
	global_load_lds_dwordx4 v138, s[34:35]
	s_mov_b32 m0, s43
	s_nop 0
	global_load_lds_dwordx4 v134, s[34:35]
	s_setprio 0
	s_waitcnt vmcnt(8)
	s_waitcnt lgkmcnt(0)
	s_barrier
	s_waitcnt lgkmcnt(0)
	v_mfma_f32_16x16x32_bf16 v[64:67], v[152:155], v[184:187], v[64:67]
	v_mfma_f32_16x16x32_bf16 v[52:55], v[160:163], v[184:187], v[52:55]
	v_mfma_f32_16x16x32_bf16 v[44:47], v[152:155], v[192:195], v[44:47]
	v_mfma_f32_16x16x32_bf16 v[36:39], v[160:163], v[192:195], v[36:39]
	v_mfma_f32_16x16x32_bf16 v[28:31], v[152:155], v[200:203], v[28:31]
	v_mfma_f32_16x16x32_bf16 v[20:23], v[160:163], v[200:203], v[20:23]
	v_mfma_f32_16x16x32_bf16 v[12:15], v[152:155], v[208:211], v[12:15]
	v_mfma_f32_16x16x32_bf16 v[2:5], v[160:163], v[208:211], v[4:7]
	v_mfma_f32_16x16x32_bf16 v[64:67], v[156:159], v[188:191], v[64:67]
	v_mfma_f32_16x16x32_bf16 v[52:55], v[164:167], v[188:191], v[52:55]
	v_mfma_f32_16x16x32_bf16 v[44:47], v[156:159], v[196:199], v[44:47]
	v_mfma_f32_16x16x32_bf16 v[36:39], v[164:167], v[196:199], v[36:39]
	v_mfma_f32_16x16x32_bf16 v[28:31], v[156:159], v[204:207], v[28:31]
	v_mfma_f32_16x16x32_bf16 v[20:23], v[164:167], v[204:207], v[20:23]
	v_mfma_f32_16x16x32_bf16 v[12:15], v[156:159], v[212:215], v[12:15]
	v_mfma_f32_16x16x32_bf16 v[2:5], v[164:167], v[212:215], v[2:5]
	v_mfma_f32_16x16x32_bf16 v[72:75], v[168:171], v[184:187], v[72:75]
	v_mfma_f32_16x16x32_bf16 v[56:59], v[176:179], v[184:187], v[56:59]
	v_mfma_f32_16x16x32_bf16 v[48:51], v[168:171], v[192:195], v[48:51]
	v_mfma_f32_16x16x32_bf16 v[40:43], v[176:179], v[192:195], v[40:43]
	v_mfma_f32_16x16x32_bf16 v[32:35], v[168:171], v[200:203], v[32:35]
	v_mfma_f32_16x16x32_bf16 v[24:27], v[176:179], v[200:203], v[24:27]
	v_mfma_f32_16x16x32_bf16 v[16:19], v[168:171], v[208:211], v[16:19]
	v_mfma_f32_16x16x32_bf16 v[6:9], v[176:179], v[208:211], v[8:11]
	v_mfma_f32_16x16x32_bf16 v[72:75], v[172:175], v[188:191], v[72:75]
	v_mfma_f32_16x16x32_bf16 v[56:59], v[180:183], v[188:191], v[56:59]
	v_mfma_f32_16x16x32_bf16 v[48:51], v[172:175], v[196:199], v[48:51]
	v_mfma_f32_16x16x32_bf16 v[40:43], v[180:183], v[196:199], v[40:43]
	v_mfma_f32_16x16x32_bf16 v[32:35], v[172:175], v[204:207], v[32:35]
	v_mfma_f32_16x16x32_bf16 v[24:27], v[180:183], v[204:207], v[24:27]
	v_mfma_f32_16x16x32_bf16 v[16:19], v[172:175], v[212:215], v[16:19]
	v_mfma_f32_16x16x32_bf16 v[8:11], v[180:183], v[212:215], v[6:9]
	s_barrier
	s_add_i32 s73, 0, 0x18000
	s_add_i32 s74, 0, 0x1c000
	v_add_u32_e32 v152, s73, v146
	v_add_u32_e32 v153, s74, v146
	ds_read_b128 v[154:157], v152
	ds_read_b128 v[158:161], v152 offset:1024
	ds_read_b128 v[162:165], v152 offset:2048
	ds_read_b128 v[166:169], v152 offset:3072
	ds_read_b128 v[170:173], v153
	ds_read_b128 v[174:177], v153 offset:1024
	ds_read_b128 v[178:181], v153 offset:2048
	ds_read_b128 v[182:185], v153 offset:3072
	s_add_u32 s30, s30, 0x40000
	s_addc_u32 s31, s31, 0
	s_mov_b32 m0, s52
	ds_read_b128 v[186:189], v149 offset:32768
	ds_read_b128 v[190:193], v149 offset:33792
	ds_read_b128 v[194:197], v149 offset:34816
	ds_read_b128 v[198:201], v149 offset:35840
	ds_read_b128 v[202:205], v149 offset:36864
	ds_read_b128 v[206:209], v149 offset:37888
	ds_read_b128 v[210:213], v149 offset:38912
	ds_read_b128 v[214:217], v149 offset:39936
	s_nop 0
	global_load_lds_dwordx4 v138, s[30:31]
	s_mov_b32 m0, s53
	s_nop 0
	global_load_lds_dwordx4 v134, s[30:31]
	s_waitcnt vmcnt(8)
	s_waitcnt lgkmcnt(0)
	s_barrier
	s_waitcnt lgkmcnt(0)
	v_mfma_f32_16x16x32_bf16 v[124:127], v[154:157], v[186:189], v[124:127]
	v_mfma_f32_16x16x32_bf16 v[116:119], v[162:165], v[186:189], v[116:119]
	v_mfma_f32_16x16x32_bf16 v[108:111], v[154:157], v[194:197], v[108:111]
	v_mfma_f32_16x16x32_bf16 v[100:103], v[162:165], v[194:197], v[100:103]
	v_mfma_f32_16x16x32_bf16 v[92:95], v[154:157], v[202:205], v[92:95]
	v_mfma_f32_16x16x32_bf16 v[84:87], v[162:165], v[202:205], v[84:87]
	v_mfma_f32_16x16x32_bf16 v[76:79], v[154:157], v[210:213], v[76:79]
	v_mfma_f32_16x16x32_bf16 v[60:63], v[162:165], v[210:213], v[60:63]
	v_mfma_f32_16x16x32_bf16 v[124:127], v[158:161], v[190:193], v[124:127]
	v_mfma_f32_16x16x32_bf16 v[116:119], v[166:169], v[190:193], v[116:119]
	v_mfma_f32_16x16x32_bf16 v[108:111], v[158:161], v[198:201], v[108:111]
	v_mfma_f32_16x16x32_bf16 v[100:103], v[166:169], v[198:201], v[100:103]
	v_mfma_f32_16x16x32_bf16 v[92:95], v[158:161], v[206:209], v[92:95]
	v_mfma_f32_16x16x32_bf16 v[84:87], v[166:169], v[206:209], v[84:87]
	v_mfma_f32_16x16x32_bf16 v[76:79], v[158:161], v[214:217], v[76:79]
	v_mfma_f32_16x16x32_bf16 v[60:63], v[166:169], v[214:217], v[60:63]
	v_mfma_f32_16x16x32_bf16 v[128:131], v[170:173], v[186:189], v[128:131]
	v_mfma_f32_16x16x32_bf16 v[120:123], v[178:181], v[186:189], v[120:123]
	v_mfma_f32_16x16x32_bf16 v[112:115], v[170:173], v[194:197], v[112:115]
	v_mfma_f32_16x16x32_bf16 v[104:107], v[178:181], v[194:197], v[104:107]
	v_mfma_f32_16x16x32_bf16 v[96:99], v[170:173], v[202:205], v[96:99]
	v_mfma_f32_16x16x32_bf16 v[88:91], v[178:181], v[202:205], v[88:91]
	v_mfma_f32_16x16x32_bf16 v[80:83], v[170:173], v[210:213], v[80:83]
	v_mfma_f32_16x16x32_bf16 v[68:71], v[178:181], v[210:213], v[68:71]
	v_mfma_f32_16x16x32_bf16 v[128:131], v[174:177], v[190:193], v[128:131]
	v_mfma_f32_16x16x32_bf16 v[120:123], v[182:185], v[190:193], v[120:123]
	v_mfma_f32_16x16x32_bf16 v[112:115], v[174:177], v[198:201], v[112:115]
	v_mfma_f32_16x16x32_bf16 v[104:107], v[182:185], v[198:201], v[104:107]
	v_mfma_f32_16x16x32_bf16 v[96:99], v[174:177], v[206:209], v[96:99]
	v_mfma_f32_16x16x32_bf16 v[88:91], v[182:185], v[206:209], v[88:91]
	v_mfma_f32_16x16x32_bf16 v[80:83], v[174:177], v[214:217], v[80:83]
	v_mfma_f32_16x16x32_bf16 v[68:71], v[182:185], v[214:217], v[68:71]
	s_barrier
; #define PG8_LDA(dst, b, h) do { _Pragma("unroll") for (int m = 0; m < 4; ++m) _Pragma("unroll") for (int k = 0; k < 2; ++k) dst[m][k] = *(const PG8_LAS bf16x8*)(lds + PG8_SA(b, h) + aoff + m * 2048 + k * 1024); } while (0)
; #define PG8_WAIT_V(n) asm volatile("s_waitcnt vmcnt(" #n ")" ::: "memory")
; template <class Epi, class Sched, bool ALIGN_EPI = false, bool SP2 = false>
; __device__ __forceinline__ void gemm_phase(PG8_LAS unsigned char* lds, const Gemm g, const Sched& S, const Epi& E, int wave_s) {
;     ...
;         for (int t = peeled ? 2 : 0; t < nt; t += 2) {
;             const bool last = (t == nt - 2);
;             const char* a1 = cA + (size_t)(t + 1) * kstep;
;             const char* a2 = last ? nA : cA + (size_t)(t + 2) * kstep; const char* b2 = last ? nB : cB + (size_t)(t + 2) * kstep;
;             const char* a3 = a2 + kstep; const char* b3 = b2 + kstep;
;             if (last && has_next) S.a_ready(nxt);
;             if constexpr (SP2) {
;             PG8_SP2_PAIR(PG8_WAIT_V8_STRICT);
;             } else {
;             PG8_LDB(B0, 0, 0); PG8_SCHED; PG8_LDA(At, 0, 0); PG8_STAGE(PG8_SA(1, 1), a1 + hstep, voffA);
;             PG8_WAIT_L(8); PG8_BAR; PG8_WAIT_L(0); PG8_MMA(0, 0, At, B0); PG8_BAR; PG8_SCHED;
;             PG8_LDB(B1, 0, 1); PG8_STAGE(PG8_SB(0, 0), b2, voffB);
;             PG8_BAR; PG8_WAIT_L(0); PG8_MMA(0, 1, At, B1); PG8_BAR;
;             PG8_LDA(At, 0, 1); PG8_STAGE(PG8_SA(0, 0), a2, voffA);
;             PG8_BAR; PG8_WAIT_L(0); PG8_MMA(1, 0, At, B0); PG8_BAR; PG8_SCHED;
;             PG8_STAGE(PG8_SB(0, 1), b2 + hstep, voffB);
;             PG8_WAIT_V(6); PG8_BAR; PG8_MMA(1, 1, At, B1); PG8_BAR;
;             PG8_LDB(B0, 1, 0); PG8_SCHED; PG8_LDA(At, 1, 0); PG8_STAGE(PG8_SA(0, 1), a2 + hstep, voffA);
;             PG8_WAIT_L(8); PG8_BAR; PG8_WAIT_L(0); PG8_MMA(0, 0, At, B0); PG8_BAR; PG8_SCHED;
;             PG8_LDB(B1, 1, 1); PG8_STAGE(PG8_SB(1, 0), b3, voffB);
;             PG8_BAR; PG8_WAIT_L(0); PG8_MMA(0, 1, At, B1); PG8_BAR;
;             PG8_LDA(At, 1, 1); PG8_STAGE(PG8_SA(1, 0), a3, voffA);
;             PG8_BAR; PG8_WAIT_L(0); PG8_MMA(1, 0, At, B0); PG8_BAR; PG8_SCHED;
;             PG8_STAGE(PG8_SB(1, 1), b3 + hstep, voffB);
;             PG8_WAIT_V(6); PG8_BAR; PG8_MMA(1, 1, At, B1); PG8_BAR;
;             }
;         }
;         if constexpr (ALIGN_EPI) { if (wr == 0) PG8_BAR; }
	s_setprio 1
	s_add_u32 s34, s28, 0x80
	s_addc_u32 s35, s29, 0
	s_add_i32 s31, s73, s38
	ds_read_b128 v[186:189], v149 offset:49152
	ds_read_b128 v[190:193], v149 offset:50176
	ds_read_b128 v[194:197], v149 offset:51200
	ds_read_b128 v[198:201], v149 offset:52224
	ds_read_b128 v[202:205], v149 offset:53248
	ds_read_b128 v[206:209], v149 offset:54272
	ds_read_b128 v[210:213], v149 offset:55296
	ds_read_b128 v[214:217], v149 offset:56320
	s_mov_b32 m0, s31
	s_add_i32 s30, s31, 0x2000
	global_load_lds_dwordx4 v136, s[34:35]
	s_mov_b64 s[98:99], s[34:35]
	s_add_u32 s34, s28, 0x40080
	s_mov_b32 m0, s30
	s_addc_u32 s35, s29, 0
	s_add_i32 s28, s74, s38
	global_load_lds_dwordx4 v132, s[98:99]
	s_mov_b32 m0, s28
	s_add_i32 s29, s28, 0x2000
	global_load_lds_dwordx4 v136, s[34:35]
	s_mov_b32 m0, s29
	s_nop 0
	global_load_lds_dwordx4 v132, s[34:35]
	s_mov_b32 m0, s54
	s_nop 0
	global_load_lds_dwordx4 v138, s[26:27]
	s_mov_b32 m0, s55
	s_nop 0
	global_load_lds_dwordx4 v134, s[26:27]
	s_setprio 0
	s_waitcnt vmcnt(8)
	s_waitcnt lgkmcnt(0)
	s_barrier
	s_waitcnt lgkmcnt(0)
	v_mfma_f32_16x16x32_bf16 v[64:67], v[154:157], v[186:189], v[64:67]
	v_mfma_f32_16x16x32_bf16 v[52:55], v[162:165], v[186:189], v[52:55]
	v_mfma_f32_16x16x32_bf16 v[44:47], v[154:157], v[194:197], v[44:47]
	v_mfma_f32_16x16x32_bf16 v[36:39], v[162:165], v[194:197], v[36:39]
	v_mfma_f32_16x16x32_bf16 v[28:31], v[154:157], v[202:205], v[28:31]
	v_mfma_f32_16x16x32_bf16 v[20:23], v[162:165], v[202:205], v[20:23]
	v_mfma_f32_16x16x32_bf16 v[12:15], v[154:157], v[210:213], v[12:15]
	v_mfma_f32_16x16x32_bf16 v[2:5], v[162:165], v[210:213], v[2:5]
	v_mfma_f32_16x16x32_bf16 v[64:67], v[158:161], v[190:193], v[64:67]
	v_mfma_f32_16x16x32_bf16 v[52:55], v[166:169], v[190:193], v[52:55]
	v_mfma_f32_16x16x32_bf16 v[44:47], v[158:161], v[198:201], v[44:47]
	v_mfma_f32_16x16x32_bf16 v[36:39], v[166:169], v[198:201], v[36:39]
	v_mfma_f32_16x16x32_bf16 v[28:31], v[158:161], v[206:209], v[28:31]
	v_mfma_f32_16x16x32_bf16 v[20:23], v[166:169], v[206:209], v[20:23]
	v_mfma_f32_16x16x32_bf16 v[12:15], v[158:161], v[214:217], v[12:15]
	v_mfma_f32_16x16x32_bf16 v[4:7], v[166:169], v[214:217], v[2:5]
	v_mfma_f32_16x16x32_bf16 v[72:75], v[170:173], v[186:189], v[72:75]
	v_mfma_f32_16x16x32_bf16 v[56:59], v[178:181], v[186:189], v[56:59]
	v_mfma_f32_16x16x32_bf16 v[48:51], v[170:173], v[194:197], v[48:51]
	v_mfma_f32_16x16x32_bf16 v[40:43], v[178:181], v[194:197], v[40:43]
	v_mfma_f32_16x16x32_bf16 v[32:35], v[170:173], v[202:205], v[32:35]
	v_mfma_f32_16x16x32_bf16 v[24:27], v[178:181], v[202:205], v[24:27]
	v_mfma_f32_16x16x32_bf16 v[16:19], v[170:173], v[210:213], v[16:19]
	v_mfma_f32_16x16x32_bf16 v[8:11], v[178:181], v[210:213], v[8:11]
	v_mfma_f32_16x16x32_bf16 v[72:75], v[174:177], v[190:193], v[72:75]
	v_mfma_f32_16x16x32_bf16 v[56:59], v[182:185], v[190:193], v[56:59]
	v_mfma_f32_16x16x32_bf16 v[48:51], v[174:177], v[198:201], v[48:51]
	v_mfma_f32_16x16x32_bf16 v[40:43], v[182:185], v[198:201], v[40:43]
	v_mfma_f32_16x16x32_bf16 v[32:35], v[174:177], v[206:209], v[32:35]
	v_mfma_f32_16x16x32_bf16 v[24:27], v[182:185], v[206:209], v[24:27]
	v_mfma_f32_16x16x32_bf16 v[16:19], v[174:177], v[214:217], v[16:19]
	v_mfma_f32_16x16x32_bf16 v[8:11], v[182:185], v[214:217], v[8:11]
	s_barrier
	s_add_i32 s70, s70, 2
	s_add_u32 s71, s71, 0x100
	s_addc_u32 s72, s72, 0
	s_cmp_gt_u32 s70, 13
	s_mov_b64 s[34:35], s[24:25]
	s_cbranch_scc0 .LBB0_2390
	s_and_b64 vcc, exec, s[12:13]
	s_cbranch_vccz .LBB0_2393
	s_cmp_eq_u32 s101, 1
	s_cbranch_scc0 .Lwok_3
	v_mbcnt_lo_u32_b32 v188, -1, 0
	v_mbcnt_hi_u32_b32 v188, -1, v188
	v_lshlrev_b32_e32 v188, 2, v188
	v_add_u32_e32 v189, 0x23400, v188
	ds_read_b32 v189, v189
	s_waitcnt lgkmcnt(0)
	v_cmp_gt_u32_e32 vcc, 13, v189
	s_nop 3
	s_and_b32 vcc_lo, vcc_lo, 0xff
	s_cmp_eq_u32 vcc_lo, 0
	s_cbranch_scc1 .Lwok_3
	s_mov_b32 s100, 0
